# adds both-groups fast tile body, one batched list read per stage for compute and prefetch tiles, and removes the LDS-DMA alias fences inside the tile streams
# speedup vs baseline: 1.0436x; 1.0209x over previous
; DEV s16x4 vtr(const LAS unsigned char* p) { typedef short v4i16_t __attribute__((ext_vector_type(4))); return __builtin_bit_cast(s16x4, __builtin_amdgcn_ds_read_tr16_b64_v4i16((LAS v4i16_t*)p)); }
; DEV unsigned cvtpk(float lo, float hi) { typedef float f2 __attribute__((ext_vector_type(2))); typedef __bf16 b2 __attribute__((ext_vector_type(2))); f2 v = {lo, hi}; b2 b = __builtin_convertvector(v, b2); return __builtin_bit_cast(unsigned, b); }
; template <bool PV, bool WITHL>
; DEV void pv64(const LAS unsigned char* Vb, const AttnCtx& C, const ab8 (&pf)[2][2], f32x4 (&O)[2][4], f32x4 (&L)[2], bool a0, bool a1) {
;     if (PV) {
;         const int vr = 4 * C.q4 + (C.n >> 2), vc = (C.n & 3) >> 1, vs = 8 * (C.n & 1);
;         ab8 vf[4][2];
; #pragma unroll
;         for (int dt = 0; dt < 4; ++dt)
; #pragma unroll
;             for (int j = 0; j < 2; ++j) {
;                 const s16x4 lo = vtr(Vb + swz(32 * j + vr, 2 * dt + vc) + vs), hi = vtr(Vb + swz(32 * j + 16 + vr, 2 * dt + vc) + vs);
;                 vf[dt][j] = __builtin_shufflevector(lo, hi, 0, 1, 2, 3, 4, 5, 6, 7); }
;         __builtin_amdgcn_sched_barrier(0);
; #pragma unroll
;         for (int dt = 0; dt < 4; ++dt)
; #pragma unroll
;             for (int j = 0; j < 2; ++j) {
;                 if (a0) O[0][dt] = __builtin_amdgcn_mfma_f32_16x16x32_bf16(vf[dt][j], pf[0][j], O[0][dt], 0, 0, 0);
;                 if (a1) O[1][dt] = __builtin_amdgcn_mfma_f32_16x16x32_bf16(vf[dt][j], pf[1][j], O[1][dt], 0, 0, 0); }
; DEV void attn_unit_mfma(Frame& F, int qg, int kv) {
;     ...
; #pragma unroll
;             for (int j = 0; j < 2; ++j) { v4u wv; wv.x = cvtpk(s[g][2 * j][0], s[g][2 * j][1]); wv.y = cvtpk(s[g][2 * j][2], s[g][2 * j][3]); wv.z = cvtpk(s[g][2 * j + 1][0], s[g][2 * j + 1][1]); wv.w = cvtpk(s[g][2 * j + 1][2], s[g][2 * j + 1][3]); pf[g][j] = __builtin_bit_cast(ab8, wv); } }
;         pv64<true, false>(Vb, C, pf, O, L, true, true);
.LBB0_942:
	s_or_b64 exec, exec, s[10:11]
	v_subrev_u32_e32 v97, s24, v179
	v_subrev_u32_e32 v102, s24, v181
	v_subrev_u32_e32 v103, s24, v182
	v_subrev_u32_e32 v114, s24, v183
	v_subrev_u32_e32 v112, s24, v184
	v_subrev_u32_e32 v110, s24, v185
	v_subrev_u32_e32 v108, s24, v186
	v_subrev_u32_e32 v106, s24, v187
	v_subrev_u32_e32 v107, s24, v188
	v_subrev_u32_e32 v109, s24, v189
	v_subrev_u32_e32 v111, s24, v190
	v_subrev_u32_e32 v113, s24, v191
	v_subrev_u32_e32 v115, s24, v192
	v_subrev_u32_e32 v116, s24, v193
	v_subrev_u32_e32 v117, s24, v194
	v_subrev_u32_e32 v118, s24, v195
	v_cvt_pk_bf16_f32 v78, v78, v79
	v_cvt_pk_bf16_f32 v79, v80, v81
	v_cvt_pk_bf16_f32 v80, v74, v75
	v_cvt_pk_bf16_f32 v81, v76, v77
	v_cvt_pk_bf16_f32 v74, v86, v87
	v_cvt_pk_bf16_f32 v75, v88, v89
	v_cvt_pk_bf16_f32 v76, v82, v83
	v_cvt_pk_bf16_f32 v77, v84, v85
	v_cvt_pk_bf16_f32 v70, v70, v71
	v_cvt_pk_bf16_f32 v71, v72, v73
	v_cvt_pk_bf16_f32 v72, v66, v67
	v_cvt_pk_bf16_f32 v73, v68, v69
	v_cvt_pk_bf16_f32 v62, v62, v63
	v_cvt_pk_bf16_f32 v63, v64, v65
	v_cvt_pk_bf16_f32 v64, v58, v59
	v_cvt_pk_bf16_f32 v65, v60, v61
	v_add3_u32 v58, s14, v118, v180
	v_add3_u32 v60, s14, v117, v180
	v_add3_u32 v66, s14, v116, v180
	v_add3_u32 v68, s14, v115, v180
	v_add3_u32 v82, s14, v113, v180
	v_add3_u32 v84, s14, v111, v180
	v_add3_u32 v86, s14, v109, v180
	v_add3_u32 v88, s14, v107, v180
	v_add3_u32 v106, s14, v106, v180
	v_add3_u32 v108, s14, v108, v180
	v_add3_u32 v110, s14, v110, v180
	v_add3_u32 v112, s14, v112, v180
	v_add3_u32 v114, s14, v114, v180
	v_add3_u32 v103, s14, v103, v180
	v_add3_u32 v102, s14, v102, v180
	v_add3_u32 v97, s14, v97, v180
	ds_read_b64_tr_b16 v[58:59], v58
	ds_read_b64_tr_b16 v[60:61], v60
	ds_read_b64_tr_b16 v[66:67], v66
	ds_read_b64_tr_b16 v[68:69], v68
	ds_read_b64_tr_b16 v[82:83], v82
	ds_read_b64_tr_b16 v[84:85], v84
	ds_read_b64_tr_b16 v[86:87], v86
	ds_read_b64_tr_b16 v[88:89], v88
	ds_read_b64_tr_b16 v[106:107], v106
	ds_read_b64_tr_b16 v[116:117], v103
	ds_read_b64_tr_b16 v[118:119], v102
	ds_read_b64_tr_b16 v[120:121], v97
	ds_read_b64_tr_b16 v[108:109], v108
	ds_read_b64_tr_b16 v[110:111], v110
	ds_read_b64_tr_b16 v[112:113], v112
	ds_read_b64_tr_b16 v[114:115], v114
	s_waitcnt lgkmcnt(14)
	v_mfma_f32_16x16x32_bf16 v[54:57], v[58:61], v[74:77], v[54:57]
	s_addk_i32 s22, 0x400
	s_addk_i32 s14, 0x4000
	s_add_i32 s86, s86, 64
	v_mfma_f32_16x16x32_bf16 v[38:41], v[58:61], v[70:73], v[38:41]
	s_add_i32 s15, s15, 1
	s_add_i32 s12, s23, -1
	v_add_u32_e32 v96, 64, v96
	s_waitcnt lgkmcnt(10)
	v_mfma_f32_16x16x32_bf16 v[46:49], v[82:85], v[74:77], v[46:49]
	v_add_u32_e32 v104, 0xfffffc00, v104
	s_cmp_eq_u32 s12, s16
	v_mfma_f32_16x16x32_bf16 v[30:33], v[82:85], v[70:73], v[30:33]
	s_waitcnt lgkmcnt(3)
	v_mfma_f32_16x16x32_bf16 v[42:45], v[106:109], v[74:77], v[42:45]
	v_mfma_f32_16x16x32_bf16 v[26:29], v[106:109], v[70:73], v[26:29]
	s_waitcnt lgkmcnt(0)
	v_mfma_f32_16x16x32_bf16 v[50:53], v[114:117], v[74:77], v[50:53]
	v_mfma_f32_16x16x32_bf16 v[34:37], v[114:117], v[70:73], v[34:37]
	v_mfma_f32_16x16x32_bf16 v[54:57], v[66:69], v[78:81], v[54:57]
	v_mfma_f32_16x16x32_bf16 v[38:41], v[66:69], v[62:65], v[38:41]
	v_mfma_f32_16x16x32_bf16 v[46:49], v[86:89], v[78:81], v[46:49]
	v_mfma_f32_16x16x32_bf16 v[30:33], v[86:89], v[62:65], v[30:33]
	v_mfma_f32_16x16x32_bf16 v[42:45], v[110:113], v[78:81], v[42:45]
	v_mfma_f32_16x16x32_bf16 v[26:29], v[110:113], v[62:65], v[26:29]
	v_mfma_f32_16x16x32_bf16 v[50:53], v[118:121], v[78:81], v[50:53]
	v_mfma_f32_16x16x32_bf16 v[34:37], v[118:121], v[62:65], v[34:37]
	s_cbranch_scc1 .LBB0_969

; #define LAS __attribute__((address_space(3)))
; DEV float dpp_xor1(float v) { return __builtin_bit_cast(float, __builtin_amdgcn_update_dpp(0, __builtin_bit_cast(int, v), 0xB1, 0xF, 0xF, true)); }
; DEV float dpp_xor2(float v) { return __builtin_bit_cast(float, __builtin_amdgcn_update_dpp(0, __builtin_bit_cast(int, v), 0x4E, 0xF, 0xF, true)); }
; DEV void attn_unit_mfma(Frame& F, int qg, int kv) {
;     ...
; #pragma unroll
;             for (int kt = 0; kt < 4; ++kt) {
; #pragma unroll
;                 for (int ii = 0; ii < 4; ++ii) s[g][kt][ii] = __builtin_amdgcn_exp2f(s[g][kt][ii]) * invl[g];
;                 float i0 = s[g][kt][0], i1 = s[g][kt][1], i2 = s[g][kt][2], i3 = s[g][kt][3];
;                 i0 += dpp_xor1(i0); i0 += dpp_xor2(i0); i1 += dpp_xor1(i1); i1 += dpp_xor2(i1); i2 += dpp_xor1(i2); i2 += dpp_xor2(i2); i3 += dpp_xor1(i3); i3 += dpp_xor2(i3);
;                 if (C.h == 0) { const int J = 16 * i + 4 * kt + C.q4; LAS float* sr = score + (8 * w + 4 * g + (C.n >> 2)) * SCS + J;
;                     __hip_atomic_fetch_add(sr, 2.f * (i0 + i1 + i2) + i3, __ATOMIC_RELAXED, __HIP_MEMORY_SCOPE_WORKGROUP); __hip_atomic_fetch_add(sr + 1, i3, __ATOMIC_RELAXED, __HIP_MEMORY_SCOPE_WORKGROUP); } }
.LBB0_951:
	v_exp_f32_e32 v86, v86
	v_exp_f32_e32 v87, v87
	v_exp_f32_e32 v88, v88
	v_exp_f32_e32 v89, v89
	v_add_u32_e32 v97, 0, v96
	v_pk_mul_f32 v[86:87], v[90:91], v[86:87]
	v_pk_mul_f32 v[88:89], v[90:91], v[88:89]
	s_nop 0
	v_add_f32_dpp v103, v86, v86 quad_perm:[1,0,3,2] row_mask:0xf bank_mask:0xf bound_ctrl:1
	v_add_f32_dpp v107, v87, v87 quad_perm:[1,0,3,2] row_mask:0xf bank_mask:0xf bound_ctrl:1
	v_add_f32_dpp v109, v88, v88 quad_perm:[1,0,3,2] row_mask:0xf bank_mask:0xf bound_ctrl:1
	v_add_f32_dpp v111, v89, v89 quad_perm:[1,0,3,2] row_mask:0xf bank_mask:0xf bound_ctrl:1
	v_mov_b32_dpp v106, v103 quad_perm:[2,3,0,1] row_mask:0xf bank_mask:0xf bound_ctrl:1
	v_mov_b32_dpp v108, v107 quad_perm:[2,3,0,1] row_mask:0xf bank_mask:0xf bound_ctrl:1
	v_mov_b32_dpp v110, v109 quad_perm:[2,3,0,1] row_mask:0xf bank_mask:0xf bound_ctrl:1
	v_mov_b32_dpp v112, v111 quad_perm:[2,3,0,1] row_mask:0xf bank_mask:0xf bound_ctrl:1
	s_and_saveexec_b64 s[12:13], s[8:9]
	s_cbranch_execz .LBB0_953
	v_add_f32_e32 v107, v107, v108
	v_add_f32_e32 v103, v103, v106
	v_add_f32_e32 v109, v109, v110
	v_add_f32_e32 v103, v103, v107
	v_add_f32_e32 v111, v111, v112
	v_add_f32_e32 v103, v103, v109
	v_fma_f32 v103, 2.0, v103, v111
	ds_add_f32 v97, v103
	ds_add_f32 v97, v111 offset:4
.LBB0_953:
	s_or_b64 exec, exec, s[12:13]
	v_exp_f32_e32 v82, v82
	v_exp_f32_e32 v83, v83
	v_exp_f32_e32 v84, v84
	v_exp_f32_e32 v85, v85
	v_pk_mul_f32 v[82:83], v[90:91], v[82:83]
	v_pk_mul_f32 v[84:85], v[90:91], v[84:85]
	s_nop 0
	v_add_f32_dpp v103, v82, v82 quad_perm:[1,0,3,2] row_mask:0xf bank_mask:0xf bound_ctrl:1
	v_add_f32_dpp v107, v83, v83 quad_perm:[1,0,3,2] row_mask:0xf bank_mask:0xf bound_ctrl:1
	v_add_f32_dpp v109, v84, v84 quad_perm:[1,0,3,2] row_mask:0xf bank_mask:0xf bound_ctrl:1
	v_add_f32_dpp v111, v85, v85 quad_perm:[1,0,3,2] row_mask:0xf bank_mask:0xf bound_ctrl:1
	v_mov_b32_dpp v106, v103 quad_perm:[2,3,0,1] row_mask:0xf bank_mask:0xf bound_ctrl:1
	v_mov_b32_dpp v108, v107 quad_perm:[2,3,0,1] row_mask:0xf bank_mask:0xf bound_ctrl:1
	v_mov_b32_dpp v110, v109 quad_perm:[2,3,0,1] row_mask:0xf bank_mask:0xf bound_ctrl:1
	v_mov_b32_dpp v112, v111 quad_perm:[2,3,0,1] row_mask:0xf bank_mask:0xf bound_ctrl:1
	s_and_saveexec_b64 s[12:13], s[8:9]
	s_cbranch_execz .LBB0_955
	v_add_f32_e32 v107, v107, v108
	v_add_f32_e32 v103, v103, v106
	v_add_f32_e32 v109, v109, v110
	v_add_f32_e32 v103, v103, v107
	v_add_f32_e32 v111, v111, v112
	v_add_f32_e32 v103, v103, v109
	v_fma_f32 v103, 2.0, v103, v111
	ds_add_f32 v97, v103 offset:16
	ds_add_f32 v97, v111 offset:20
.LBB0_955:
	s_or_b64 exec, exec, s[12:13]
	v_exp_f32_e32 v78, v78
	v_exp_f32_e32 v79, v79
	v_exp_f32_e32 v80, v80
	v_exp_f32_e32 v81, v81
	v_pk_mul_f32 v[78:79], v[90:91], v[78:79]
	v_pk_mul_f32 v[80:81], v[90:91], v[80:81]
	s_nop 0
	v_add_f32_dpp v103, v78, v78 quad_perm:[1,0,3,2] row_mask:0xf bank_mask:0xf bound_ctrl:1
	v_add_f32_dpp v107, v79, v79 quad_perm:[1,0,3,2] row_mask:0xf bank_mask:0xf bound_ctrl:1
	v_add_f32_dpp v109, v80, v80 quad_perm:[1,0,3,2] row_mask:0xf bank_mask:0xf bound_ctrl:1
	v_add_f32_dpp v111, v81, v81 quad_perm:[1,0,3,2] row_mask:0xf bank_mask:0xf bound_ctrl:1
	v_mov_b32_dpp v106, v103 quad_perm:[2,3,0,1] row_mask:0xf bank_mask:0xf bound_ctrl:1
	v_mov_b32_dpp v108, v107 quad_perm:[2,3,0,1] row_mask:0xf bank_mask:0xf bound_ctrl:1
	v_mov_b32_dpp v110, v109 quad_perm:[2,3,0,1] row_mask:0xf bank_mask:0xf bound_ctrl:1
	v_mov_b32_dpp v112, v111 quad_perm:[2,3,0,1] row_mask:0xf bank_mask:0xf bound_ctrl:1
	s_and_saveexec_b64 s[12:13], s[8:9]
	s_cbranch_execz .LBB0_957
	v_add_f32_e32 v107, v107, v108
	v_add_f32_e32 v103, v103, v106
	v_add_f32_e32 v109, v109, v110
	v_add_f32_e32 v103, v103, v107
	v_add_f32_e32 v111, v111, v112
	v_add_f32_e32 v103, v103, v109
	v_fma_f32 v103, 2.0, v103, v111
	ds_add_f32 v97, v103 offset:32
	ds_add_f32 v97, v111 offset:36
.LBB0_957:
	s_or_b64 exec, exec, s[12:13]
	v_exp_f32_e32 v74, v74
	v_exp_f32_e32 v75, v75
	v_exp_f32_e32 v76, v76
	v_exp_f32_e32 v77, v77
	v_pk_mul_f32 v[74:75], v[90:91], v[74:75]
	v_pk_mul_f32 v[76:77], v[90:91], v[76:77]
	s_nop 0
	v_add_f32_dpp v103, v74, v74 quad_perm:[1,0,3,2] row_mask:0xf bank_mask:0xf bound_ctrl:1
	v_add_f32_dpp v107, v75, v75 quad_perm:[1,0,3,2] row_mask:0xf bank_mask:0xf bound_ctrl:1
	v_add_f32_dpp v109, v76, v76 quad_perm:[1,0,3,2] row_mask:0xf bank_mask:0xf bound_ctrl:1
	v_add_f32_dpp v111, v77, v77 quad_perm:[1,0,3,2] row_mask:0xf bank_mask:0xf bound_ctrl:1
	v_mov_b32_dpp v106, v103 quad_perm:[2,3,0,1] row_mask:0xf bank_mask:0xf bound_ctrl:1
	v_mov_b32_dpp v108, v107 quad_perm:[2,3,0,1] row_mask:0xf bank_mask:0xf bound_ctrl:1
	v_mov_b32_dpp v110, v109 quad_perm:[2,3,0,1] row_mask:0xf bank_mask:0xf bound_ctrl:1
	v_mov_b32_dpp v112, v111 quad_perm:[2,3,0,1] row_mask:0xf bank_mask:0xf bound_ctrl:1
	s_and_saveexec_b64 s[12:13], s[8:9]
	s_cbranch_execz .LBB0_959
	v_add_f32_e32 v107, v107, v108
	v_add_f32_e32 v103, v103, v106
	v_add_f32_e32 v109, v109, v110
	v_add_f32_e32 v103, v103, v107
	v_add_f32_e32 v111, v111, v112
	v_add_f32_e32 v103, v103, v109
	v_fma_f32 v103, 2.0, v103, v111
	ds_add_f32 v97, v103 offset:48
	ds_add_f32 v97, v111 offset:52

; #define LAS __attribute__((address_space(3)))
; DEV float dpp_xor1(float v) { return __builtin_bit_cast(float, __builtin_amdgcn_update_dpp(0, __builtin_bit_cast(int, v), 0xB1, 0xF, 0xF, true)); }
; DEV float dpp_xor2(float v) { return __builtin_bit_cast(float, __builtin_amdgcn_update_dpp(0, __builtin_bit_cast(int, v), 0x4E, 0xF, 0xF, true)); }
; DEV void attn_unit_mfma(Frame& F, int qg, int kv) {
;     ...
; #pragma unroll
;             for (int kt = 0; kt < 4; ++kt) {
; #pragma unroll
;                 for (int ii = 0; ii < 4; ++ii) s[g][kt][ii] = __builtin_amdgcn_exp2f(s[g][kt][ii]) * invl[g];
;                 float i0 = s[g][kt][0], i1 = s[g][kt][1], i2 = s[g][kt][2], i3 = s[g][kt][3];
;                 i0 += dpp_xor1(i0); i0 += dpp_xor2(i0); i1 += dpp_xor1(i1); i1 += dpp_xor2(i1); i2 += dpp_xor1(i2); i2 += dpp_xor2(i2); i3 += dpp_xor1(i3); i3 += dpp_xor2(i3);
;                 if (C.h == 0) { const int J = 16 * i + 4 * kt + C.q4; LAS float* sr = score + (8 * w + 4 * g + (C.n >> 2)) * SCS + J;
;                     __hip_atomic_fetch_add(sr, 2.f * (i0 + i1 + i2) + i3, __ATOMIC_RELAXED, __HIP_MEMORY_SCOPE_WORKGROUP); __hip_atomic_fetch_add(sr + 1, i3, __ATOMIC_RELAXED, __HIP_MEMORY_SCOPE_WORKGROUP); } }
.LBB0_961:
	v_exp_f32_e32 v70, v70
	v_exp_f32_e32 v71, v71
	v_exp_f32_e32 v72, v72
	v_exp_f32_e32 v73, v73
	v_pk_mul_f32 v[70:71], v[92:93], v[70:71]
	v_pk_mul_f32 v[72:73], v[92:93], v[72:73]
	s_nop 0
	v_add_f32_dpp v102, v70, v70 quad_perm:[1,0,3,2] row_mask:0xf bank_mask:0xf bound_ctrl:1
	v_add_f32_dpp v106, v71, v71 quad_perm:[1,0,3,2] row_mask:0xf bank_mask:0xf bound_ctrl:1
	v_add_f32_dpp v108, v72, v72 quad_perm:[1,0,3,2] row_mask:0xf bank_mask:0xf bound_ctrl:1
	v_add_f32_dpp v110, v73, v73 quad_perm:[1,0,3,2] row_mask:0xf bank_mask:0xf bound_ctrl:1
	v_mov_b32_dpp v103, v102 quad_perm:[2,3,0,1] row_mask:0xf bank_mask:0xf bound_ctrl:1
	v_mov_b32_dpp v107, v106 quad_perm:[2,3,0,1] row_mask:0xf bank_mask:0xf bound_ctrl:1
	v_mov_b32_dpp v109, v108 quad_perm:[2,3,0,1] row_mask:0xf bank_mask:0xf bound_ctrl:1
	v_mov_b32_dpp v111, v110 quad_perm:[2,3,0,1] row_mask:0xf bank_mask:0xf bound_ctrl:1
	s_and_saveexec_b64 s[10:11], s[8:9]
	s_cbranch_execz .LBB0_963
	v_add_f32_e32 v106, v106, v107
	v_add_f32_e32 v102, v102, v103
	v_add_f32_e32 v108, v108, v109
	v_add_f32_e32 v102, v102, v106
	v_add_f32_e32 v110, v110, v111
	v_add_f32_e32 v102, v102, v108
	v_fma_f32 v102, 2.0, v102, v110
	ds_add_f32 v97, v102 offset:4160
	ds_add_f32 v97, v110 offset:4164
.LBB0_963:
	s_or_b64 exec, exec, s[10:11]
	v_exp_f32_e32 v66, v66
	v_exp_f32_e32 v67, v67
	v_exp_f32_e32 v68, v68
	v_exp_f32_e32 v69, v69
	v_pk_mul_f32 v[66:67], v[92:93], v[66:67]
	v_pk_mul_f32 v[68:69], v[92:93], v[68:69]
	s_nop 0
	v_add_f32_dpp v102, v66, v66 quad_perm:[1,0,3,2] row_mask:0xf bank_mask:0xf bound_ctrl:1
	v_add_f32_dpp v106, v67, v67 quad_perm:[1,0,3,2] row_mask:0xf bank_mask:0xf bound_ctrl:1
	v_add_f32_dpp v108, v68, v68 quad_perm:[1,0,3,2] row_mask:0xf bank_mask:0xf bound_ctrl:1
	v_add_f32_dpp v110, v69, v69 quad_perm:[1,0,3,2] row_mask:0xf bank_mask:0xf bound_ctrl:1
	v_mov_b32_dpp v103, v102 quad_perm:[2,3,0,1] row_mask:0xf bank_mask:0xf bound_ctrl:1
	v_mov_b32_dpp v107, v106 quad_perm:[2,3,0,1] row_mask:0xf bank_mask:0xf bound_ctrl:1
	v_mov_b32_dpp v109, v108 quad_perm:[2,3,0,1] row_mask:0xf bank_mask:0xf bound_ctrl:1
	v_mov_b32_dpp v111, v110 quad_perm:[2,3,0,1] row_mask:0xf bank_mask:0xf bound_ctrl:1
	s_and_saveexec_b64 s[10:11], s[8:9]
	s_cbranch_execz .LBB0_965
	v_add_f32_e32 v106, v106, v107
	v_add_f32_e32 v102, v102, v103
	v_add_f32_e32 v108, v108, v109
	v_add_f32_e32 v102, v102, v106
	v_add_f32_e32 v110, v110, v111
	v_add_f32_e32 v102, v102, v108
	v_fma_f32 v102, 2.0, v102, v110
	ds_add_f32 v97, v102 offset:4176
	ds_add_f32 v97, v110 offset:4180
.LBB0_965:
	s_or_b64 exec, exec, s[10:11]
	v_exp_f32_e32 v62, v62
	v_exp_f32_e32 v63, v63
	v_exp_f32_e32 v64, v64
	v_exp_f32_e32 v65, v65
	v_pk_mul_f32 v[62:63], v[92:93], v[62:63]
	v_pk_mul_f32 v[64:65], v[92:93], v[64:65]
	s_nop 0
	v_add_f32_dpp v102, v62, v62 quad_perm:[1,0,3,2] row_mask:0xf bank_mask:0xf bound_ctrl:1
	v_add_f32_dpp v106, v63, v63 quad_perm:[1,0,3,2] row_mask:0xf bank_mask:0xf bound_ctrl:1
	v_add_f32_dpp v108, v64, v64 quad_perm:[1,0,3,2] row_mask:0xf bank_mask:0xf bound_ctrl:1
	v_add_f32_dpp v110, v65, v65 quad_perm:[1,0,3,2] row_mask:0xf bank_mask:0xf bound_ctrl:1
	v_mov_b32_dpp v103, v102 quad_perm:[2,3,0,1] row_mask:0xf bank_mask:0xf bound_ctrl:1
	v_mov_b32_dpp v107, v106 quad_perm:[2,3,0,1] row_mask:0xf bank_mask:0xf bound_ctrl:1
	v_mov_b32_dpp v109, v108 quad_perm:[2,3,0,1] row_mask:0xf bank_mask:0xf bound_ctrl:1
	v_mov_b32_dpp v111, v110 quad_perm:[2,3,0,1] row_mask:0xf bank_mask:0xf bound_ctrl:1
	s_and_saveexec_b64 s[10:11], s[8:9]
	s_cbranch_execz .LBB0_967
	v_add_f32_e32 v106, v106, v107
	v_add_f32_e32 v102, v102, v103
	v_add_f32_e32 v108, v108, v109
	v_add_f32_e32 v102, v102, v106
	v_add_f32_e32 v110, v110, v111
	v_add_f32_e32 v102, v102, v108
	v_fma_f32 v102, 2.0, v102, v110
	ds_add_f32 v97, v102 offset:4192
	ds_add_f32 v97, v110 offset:4196
.LBB0_967:
	s_or_b64 exec, exec, s[10:11]
	v_exp_f32_e32 v58, v58
	v_exp_f32_e32 v59, v59
	v_exp_f32_e32 v60, v60
	v_exp_f32_e32 v61, v61
	v_pk_mul_f32 v[58:59], v[92:93], v[58:59]
	v_pk_mul_f32 v[60:61], v[92:93], v[60:61]
	s_nop 0
	v_add_f32_dpp v102, v58, v58 quad_perm:[1,0,3,2] row_mask:0xf bank_mask:0xf bound_ctrl:1
	v_add_f32_dpp v106, v59, v59 quad_perm:[1,0,3,2] row_mask:0xf bank_mask:0xf bound_ctrl:1
	v_add_f32_dpp v108, v60, v60 quad_perm:[1,0,3,2] row_mask:0xf bank_mask:0xf bound_ctrl:1
	v_add_f32_dpp v110, v61, v61 quad_perm:[1,0,3,2] row_mask:0xf bank_mask:0xf bound_ctrl:1
	v_mov_b32_dpp v103, v102 quad_perm:[2,3,0,1] row_mask:0xf bank_mask:0xf bound_ctrl:1
	v_mov_b32_dpp v107, v106 quad_perm:[2,3,0,1] row_mask:0xf bank_mask:0xf bound_ctrl:1
	v_mov_b32_dpp v109, v108 quad_perm:[2,3,0,1] row_mask:0xf bank_mask:0xf bound_ctrl:1
	v_mov_b32_dpp v111, v110 quad_perm:[2,3,0,1] row_mask:0xf bank_mask:0xf bound_ctrl:1
	s_and_saveexec_b64 s[10:11], s[8:9]
	s_cbranch_execz .LBB0_942
	v_add_f32_e32 v106, v106, v107
	v_add_f32_e32 v102, v102, v103
	v_add_f32_e32 v108, v108, v109
	v_add_f32_e32 v102, v102, v106
	v_add_f32_e32 v110, v110, v111
	v_add_f32_e32 v102, v102, v108
	v_fma_f32 v102, 2.0, v102, v110
	ds_add_f32 v97, v102 offset:4208
	ds_add_f32 v97, v110 offset:4212
	s_branch .LBB0_942

; #define LAS __attribute__((address_space(3)))
; #define SS_ISSUE(t, slot) do { LAS unsigned char* d_ = lbase + (slot) * 2 * TILEB; const size_t gb_ = (size_t)rowfn(t) * 256 + goff; \
;         __builtin_amdgcn_global_load_lds((const unsigned*)((const char*)Kg + gb_), (LAS unsigned*)d_, 16, 0, 0); \
;         __builtin_amdgcn_global_load_lds((const unsigned*)((const char*)Vg + gb_), (LAS unsigned*)(d_ + TILEB), 16, 0, 0); } while (0)
; template <int NB, class RowFn, class Compute>
; DEV void stream_stages_dma(Frame& F, int n, const bf16* Kg, const bf16* Vg, RowFn rowfn, Compute compute) {
;     ...
; #pragma unroll
;     for (int b = 0; b < NB; ++b) if (b < n) SS_ISSUE(b, b);
;     for (int i0 = 0, st = 0; i0 < n; i0 += NB, st ^= 1) {
;         asm volatile("s_waitcnt vmcnt(0)" ::: "memory");
;         __builtin_amdgcn_s_barrier(); asm volatile("" ::: "memory");
; #pragma unroll
;         for (int b = 0; b < NB; ++b) if (i0 + NB + b < n) SS_ISSUE(i0 + NB + b, (st ^ 1) * NB + b);
;         const LAS unsigned char* cur = F.lds + st * NB * 2 * TILEB;
; #pragma unroll
;         for (int b = 0; b < NB; ++b) if (i0 + b < n) compute(i0 + b, cur + b * 2 * TILEB, cur + b * 2 * TILEB + TILEB);
; DEV void attn_unit_mfma(Frame& F, int qg, int kv) {
;     ...
;         const int j = lst[1 + i]; const unsigned byte = (msk[2 * j + (w >> 2)] >> (8 * (w & 3))) & 0xffu;
.LBB0_1167:
	s_waitcnt vmcnt(0)
	s_barrier
	s_xor_b32 s25, s8, 1
	s_mul_i32 s9, s25, 0xc000
	s_add_i32 s9, s51, s9
	s_add_i32 s26, s28, 3
	v_mov_b32_e32 v66, s24
	ds_read_b32 v67, v66
	ds_read_b32 v68, v66 offset:4
	ds_read_b32 v69, v66 offset:8
	ds_read_b32 v73, v66 offset:12
	ds_read_b32 v74, v66 offset:16
	ds_read_b32 v75, v66 offset:20
	s_waitcnt lgkmcnt(0)
	v_lshl_add_u32 v70, v67, 3, s2
	v_lshl_add_u32 v71, v68, 3, s2
	v_lshl_add_u32 v72, v69, 3, s2
	ds_read_b32 v70, v70
	ds_read_b32 v71, v71
	ds_read_b32 v72, v72
	s_add_i32 s10, s28, 1
	s_cmp_ge_i32 s10, s23
	s_cbranch_scc1 .Lmy_sel_dma_done
	v_lshlrev_b32_e32 v76, 6, v73
	v_ashrrev_i32_e32 v77, 31, v76
	v_lshlrev_b64 v[76:77], 8, v[76:77]
	v_lshl_add_u64 v[76:77], v[76:77], 0, v[156:157]
	s_mov_b32 m0, s9
	v_lshl_add_u64 v[78:79], s[92:93], 0, v[76:77]
	global_load_lds_dwordx4 v[78:79], off
	v_lshl_add_u64 v[76:77], s[48:49], 0, v[76:77]
	s_add_i32 m0, s9, 0x2000
	s_nop 0
	global_load_lds_dwordx4 v[76:77], off
	s_add_i32 s10, s28, 2
	s_cmp_ge_i32 s10, s23
	s_cbranch_scc1 .Lmy_sel_dma_done
	v_lshlrev_b32_e32 v76, 6, v74
	v_ashrrev_i32_e32 v77, 31, v76
	v_lshlrev_b64 v[76:77], 8, v[76:77]
	v_lshl_add_u64 v[76:77], v[76:77], 0, v[156:157]
	s_add_i32 m0, s9, 0x4000
	v_lshl_add_u64 v[78:79], s[92:93], 0, v[76:77]
	global_load_lds_dwordx4 v[78:79], off
	v_lshl_add_u64 v[76:77], s[48:49], 0, v[76:77]
	s_add_i32 m0, s9, 0x6000
	s_nop 0
	global_load_lds_dwordx4 v[76:77], off
	s_cmp_ge_i32 s26, s23
	s_cbranch_scc1 .Lmy_sel_dma_done
	v_lshlrev_b32_e32 v76, 6, v75
	v_ashrrev_i32_e32 v77, 31, v76
	v_lshlrev_b64 v[76:77], 8, v[76:77]
	v_lshl_add_u64 v[76:77], v[76:77], 0, v[156:157]
	s_add_i32 m0, s9, 0x8000
	v_lshl_add_u64 v[78:79], s[92:93], 0, v[76:77]
	global_load_lds_dwordx4 v[78:79], off
	v_lshl_add_u64 v[76:77], s[48:49], 0, v[76:77]
	s_add_i32 m0, s9, 0xa000
	s_nop 0
	global_load_lds_dwordx4 v[76:77], off
.Lmy_sel_dma_done:
	v_readfirstlane_b32 s98, v67
	v_readfirstlane_b32 s99, v68
	v_readfirstlane_b32 s100, v69
	s_waitcnt lgkmcnt(0)
	v_readfirstlane_b32 s9, v70
	v_readfirstlane_b32 s10, v71
	v_readfirstlane_b32 s11, v72
	s_and_b32 s98, s98, 0xffff
	s_and_b32 s99, s99, 0xffff
	s_and_b32 s100, s100, 0xffff
	s_lshr_b32 s9, s9, s33
	s_and_b32 s9, s9, 0xff
	s_lshl_b32 s9, s9, 16
	s_or_b32 s98, s98, s9
	s_lshr_b32 s10, s10, s33
	s_and_b32 s10, s10, 0xff
	s_lshl_b32 s10, s10, 16
	s_or_b32 s99, s99, s10
	s_lshr_b32 s11, s11, s33
	s_and_b32 s11, s11, 0xff
	s_lshl_b32 s11, s11, 16
	s_or_b32 s100, s100, s11
	s_lshr_b32 s9, s98, 16
	s_cmp_lg_u32 s9, 0
	s_cselect_b32 s9, 1, 0
	s_lshr_b32 s10, s99, 16
	s_cmp_lg_u32 s10, 0
	s_cselect_b32 s10, 1, 0
	s_lshr_b32 s11, s100, 16
	s_cmp_lg_u32 s11, 0
	s_cselect_b32 s11, 1, 0
	s_add_i32 s12, s28, -1
	s_cmp_lt_i32 s12, s23
	s_cselect_b32 s10, s10, 0
	s_cmp_lt_i32 s28, s23
	s_cselect_b32 s11, s11, 0
	s_add_i32 s9, s9, s10
	s_add_i32 s9, s9, s11
	s_cmp_ge_u32 s9, 3
	s_cbranch_scc0 .Lmy_sel_p2
	s_setprio 2
	s_branch .Lmy_sel_pd

; DEV void qk64(const LAS unsigned char* Kb, const AttnCtx& C, const ab8 (&qf)[2][2], f32x4 (&s)[2][4], float init0, float init1, bool a0, bool a1) {
;     ab8 k0[4], k1[4];
; #pragma unroll
;     for (int kt = 0; kt < 4; ++kt) { k0[kt] = *(const LAS ab8*)(Kb + swz(16 * kt + C.n, C.q4)); k1[kt] = *(const LAS ab8*)(Kb + swz(16 * kt + C.n, 4 + C.q4)); }
;     __builtin_amdgcn_sched_barrier(0);
; #pragma unroll
;     for (int kt = 0; kt < 4; ++kt) {
;         if (a0) { f32x4 c = {init0, init0, init0, init0}; c = __builtin_amdgcn_mfma_f32_16x16x32_bf16(k0[kt], qf[0][0], c, 0, 0, 0); s[0][kt] = __builtin_amdgcn_mfma_f32_16x16x32_bf16(k1[kt], qf[0][1], c, 0, 0, 0); }
;         if (a1) { f32x4 c = {init1, init1, init1, init1}; c = __builtin_amdgcn_mfma_f32_16x16x32_bf16(k0[kt], qf[1][0], c, 0, 0, 0); s[1][kt] = __builtin_amdgcn_mfma_f32_16x16x32_bf16(k1[kt], qf[1][1], c, 0, 0, 0); }
; DEV void ref_step(f32x4 (&s)[4], float& m, f32x4 (&O)[4], f32x4& L, ab8 (&pf)[2], bool colact) {
;     ...
;     const bool slow = (colact && m == NEG_INF) || mx > 64.f;
;     if (__any(slow)) {
;         mx = fmaxf(mx, __shfl_xor(mx, 16)); mx = fmaxf(mx, __shfl_xor(mx, 32));
;         const bool un = (m == NEG_INF);
;         const float d = (mx == NEG_INF) ? 0.f : (un ? mx : fmaxf(mx, 0.f));
;         const float sc = un ? 1.f : __builtin_amdgcn_exp2f(-d);
; #pragma unroll
;         for (int kt = 0; kt < 4; ++kt) s[kt] = s[kt] - d;
; #pragma unroll
;         for (int dt = 0; dt < 4; ++dt) O[dt] = O[dt] * sc;
;         L = L * sc;
;         m = un ? ((mx == NEG_INF) ? NEG_INF : mx) : m + d;
;     }
; #pragma unroll
;     for (int kt = 0; kt < 4; ++kt)
; #pragma unroll
;         for (int i = 0; i < 4; ++i) s[kt][i] = __builtin_amdgcn_exp2f(s[kt][i]);
; #pragma unroll
;     for (int j = 0; j < 2; ++j) { v4u w; w.x = cvtpk(s[2 * j][0], s[2 * j][1]); w.y = cvtpk(s[2 * j][2], s[2 * j][3]); w.z = cvtpk(s[2 * j + 1][0], s[2 * j + 1][1]); w.w = cvtpk(s[2 * j + 1][2], s[2 * j + 1][3]); pf[j] = __builtin_bit_cast(ab8, w); }
; }
; template <bool PV, bool WITHL>
; DEV void pv64(const LAS unsigned char* Vb, const AttnCtx& C, const ab8 (&pf)[2][2], f32x4 (&O)[2][4], f32x4 (&L)[2], bool a0, bool a1) {
;     if (PV) {
;         const int vr = 4 * C.q4 + (C.n >> 2), vc = (C.n & 3) >> 1, vs = 8 * (C.n & 1);
;         ab8 vf[4][2];
; #pragma unroll
;         for (int dt = 0; dt < 4; ++dt)
; #pragma unroll
.Lmy_sel_pd:
.LBB0_1171:
	s_mul_i32 s8, s8, 0xc000
	s_add_i32 s9, s28, -2
	s_add_i32 s27, s8, 0
	s_cmp_ge_i32 s9, s23
	s_cbranch_scc1 .LBB0_1196
	s_waitcnt lgkmcnt(0)
	s_and_b32 s29, s98, 0xffff
	s_lshr_b32 s8, s98, 16
	s_and_b32 s9, s8, 0xff
	s_cmp_eq_u32 s9, 0
	s_cbranch_scc1 .LBB0_1196
	s_cmp_ge_i32 s29, s22
	s_cbranch_scc1 .Lmy_orig_0
	s_and_b32 s9, s8, 15
	s_and_b32 s10, s8, 0xf0
	s_cmp_lg_u32 s9, 0
	s_cselect_b32 s11, 1, 0
	s_cmp_lg_u32 s10, 0
	s_cselect_b32 s12, 1, 0
	s_add_i32 s13, s11, s12
	s_cmp_eq_u32 s13, 2
	s_cbranch_scc1 .Lmy_fb_0
	s_cmp_eq_u32 s11, 1
	s_cbranch_scc0 .Lmy_f1_0
	v_add3_u32 v228, s27, v199, v198
	v_add3_u32 v229, s27, v197, v198
	ds_read_b128 v[66:69], v228 offset:0
	ds_read_b128 v[70:73], v229 offset:0
	ds_read_b128 v[74:77], v228 offset:2048
	ds_read_b128 v[78:81], v229 offset:2048
	ds_read_b128 v[82:85], v228 offset:4096
	ds_read_b128 v[86:89], v229 offset:4096
	ds_read_b128 v[90:93], v228 offset:6144
	ds_read_b128 v[94:97], v229 offset:6144
	v_and_b32_e32 v239, s8, v206
	v_cmp_ne_u32_e64 s[10:11], 0, v239
	v_cmp_eq_f32_e64 s[12:13], s3, v213
	v_add_u32_e32 v234, s27, v200
	v_add3_u32 v235, v234, v201, v209
	v_add3_u32 v236, v234, v202, v209
	v_cndmask_b32_e64 v230, v213, 0, s[12:13]
	v_sub_f32_e32 v230, v175, v230
	v_add3_u32 v237, v234, v203, v209
	v_add3_u32 v238, v234, v204, v209
	v_cndmask_b32_e64 v230, v173, v230, s[10:11]
	s_and_b64 s[12:13], s[10:11], s[12:13]
	v_mov_b32_e32 v231, v230
	v_mov_b32_e32 v232, v230
	v_mov_b32_e32 v233, v230
	s_waitcnt lgkmcnt(0)
	v_mfma_f32_16x16x32_bf16 v[66:69], v[66:69], v[2:5], v[230:233]
	v_mfma_f32_16x16x32_bf16 v[74:77], v[74:77], v[2:5], v[230:233]
	v_mfma_f32_16x16x32_bf16 v[82:85], v[82:85], v[2:5], v[230:233]
	v_mfma_f32_16x16x32_bf16 v[90:93], v[90:93], v[2:5], v[230:233]
	v_mfma_f32_16x16x32_bf16 v[66:69], v[70:73], v[6:9], v[66:69]
	v_mfma_f32_16x16x32_bf16 v[74:77], v[78:81], v[6:9], v[74:77]
	v_mfma_f32_16x16x32_bf16 v[82:85], v[86:89], v[6:9], v[82:85]
	v_mfma_f32_16x16x32_bf16 v[90:93], v[94:97], v[6:9], v[90:93]
	ds_read_b64_tr_b16 v[98:99], v235 offset:8192
	ds_read_b64_tr_b16 v[100:101], v235 offset:10240
	ds_read_b64_tr_b16 v[102:103], v235 offset:12288
	ds_read_b64_tr_b16 v[104:105], v235 offset:14336
	ds_read_b64_tr_b16 v[106:107], v236 offset:8192
	ds_read_b64_tr_b16 v[108:109], v236 offset:10240
	ds_read_b64_tr_b16 v[110:111], v236 offset:12288
	ds_read_b64_tr_b16 v[112:113], v236 offset:14336
	ds_read_b64_tr_b16 v[114:115], v237 offset:8192
	ds_read_b64_tr_b16 v[116:117], v237 offset:10240
	ds_read_b64_tr_b16 v[118:119], v237 offset:12288
	ds_read_b64_tr_b16 v[120:121], v237 offset:14336
	ds_read_b64_tr_b16 v[122:123], v238 offset:8192
	ds_read_b64_tr_b16 v[124:125], v238 offset:10240
	ds_read_b64_tr_b16 v[126:127], v238 offset:12288
	ds_read_b64_tr_b16 v[128:129], v238 offset:14336
	v_max3_f32 v239, v66, v67, v68
	v_max3_f32 v240, v69, v74, v75
	v_max3_f32 v241, v76, v77, v82
	v_max3_f32 v242, v83, v84, v85
	v_max3_f32 v239, v239, v240, v90
	v_max3_f32 v241, v241, v242, v91
	v_max3_f32 v239, v239, v92, v93
	v_max_f32_e32 v239, v239, v241
	v_cmp_lt_f32_e32 vcc, s96, v239
	s_or_b64 s[12:13], s[12:13], vcc
	s_cmp_lg_u64 s[12:13], 0
	s_cbranch_scc1 .Lmy_slow_0_0
	v_exp_f32_e32 v66, v66
	v_exp_f32_e32 v67, v67
	v_exp_f32_e32 v68, v68
	v_exp_f32_e32 v69, v69
	v_exp_f32_e32 v74, v74
	v_exp_f32_e32 v75, v75
	v_exp_f32_e32 v76, v76
	v_exp_f32_e32 v77, v77
	v_exp_f32_e32 v82, v82
	v_exp_f32_e32 v83, v83
	v_exp_f32_e32 v84, v84
	v_exp_f32_e32 v85, v85
	v_exp_f32_e32 v90, v90
	v_exp_f32_e32 v91, v91
	v_exp_f32_e32 v92, v92
	v_exp_f32_e32 v93, v93
	v_cvt_pk_bf16_f32 v130, v66, v67
	v_cvt_pk_bf16_f32 v131, v68, v69
	v_cvt_pk_bf16_f32 v132, v74, v75
	v_cvt_pk_bf16_f32 v133, v76, v77
	v_cvt_pk_bf16_f32 v134, v82, v83
	v_cvt_pk_bf16_f32 v135, v84, v85
	v_cvt_pk_bf16_f32 v136, v90, v91
	v_cvt_pk_bf16_f32 v137, v92, v93
	s_nop 1
	s_waitcnt lgkmcnt(12)
	v_mfma_f32_16x16x32_bf16 v[62:65], v[98:101], v[130:133], v[62:65]
	v_mfma_f32_16x16x32_bf16 v[58:61], v[22:25], v[130:133], v[58:61]
	v_mfma_f32_16x16x32_bf16 v[62:65], v[102:105], v[134:137], v[62:65]
	s_waitcnt lgkmcnt(8)
	v_mfma_f32_16x16x32_bf16 v[54:57], v[106:109], v[130:133], v[54:57]
	v_mfma_f32_16x16x32_bf16 v[54:57], v[110:113], v[134:137], v[54:57]
	s_waitcnt lgkmcnt(4)
	v_mfma_f32_16x16x32_bf16 v[50:53], v[114:117], v[130:133], v[50:53]
	v_mfma_f32_16x16x32_bf16 v[58:61], v[22:25], v[134:137], v[58:61]
	v_mfma_f32_16x16x32_bf16 v[50:53], v[118:121], v[134:137], v[50:53]
	s_waitcnt lgkmcnt(0)
	v_mfma_f32_16x16x32_bf16 v[46:49], v[122:125], v[130:133], v[46:49]
	v_mfma_f32_16x16x32_bf16 v[46:49], v[126:129], v[134:137], v[46:49]
	s_nop 7
	s_branch .LBB0_1196

; DEV void qk64(const LAS unsigned char* Kb, const AttnCtx& C, const ab8 (&qf)[2][2], f32x4 (&s)[2][4], float init0, float init1, bool a0, bool a1) {
;     ab8 k0[4], k1[4];
; #pragma unroll
;     for (int kt = 0; kt < 4; ++kt) { k0[kt] = *(const LAS ab8*)(Kb + swz(16 * kt + C.n, C.q4)); k1[kt] = *(const LAS ab8*)(Kb + swz(16 * kt + C.n, 4 + C.q4)); }
;     __builtin_amdgcn_sched_barrier(0);
; #pragma unroll
;     for (int kt = 0; kt < 4; ++kt) {
;         if (a0) { f32x4 c = {init0, init0, init0, init0}; c = __builtin_amdgcn_mfma_f32_16x16x32_bf16(k0[kt], qf[0][0], c, 0, 0, 0); s[0][kt] = __builtin_amdgcn_mfma_f32_16x16x32_bf16(k1[kt], qf[0][1], c, 0, 0, 0); }
;         if (a1) { f32x4 c = {init1, init1, init1, init1}; c = __builtin_amdgcn_mfma_f32_16x16x32_bf16(k0[kt], qf[1][0], c, 0, 0, 0); s[1][kt] = __builtin_amdgcn_mfma_f32_16x16x32_bf16(k1[kt], qf[1][1], c, 0, 0, 0); }
; DEV void ref_step(f32x4 (&s)[4], float& m, f32x4 (&O)[4], f32x4& L, ab8 (&pf)[2], bool colact) {
;     ...
;     const bool slow = (colact && m == NEG_INF) || mx > 64.f;
;     if (__any(slow)) {
;         mx = fmaxf(mx, __shfl_xor(mx, 16)); mx = fmaxf(mx, __shfl_xor(mx, 32));
;         const bool un = (m == NEG_INF);
;         const float d = (mx == NEG_INF) ? 0.f : (un ? mx : fmaxf(mx, 0.f));
;         const float sc = un ? 1.f : __builtin_amdgcn_exp2f(-d);
; #pragma unroll
;         for (int kt = 0; kt < 4; ++kt) s[kt] = s[kt] - d;
; #pragma unroll
;         for (int dt = 0; dt < 4; ++dt) O[dt] = O[dt] * sc;
;         L = L * sc;
;         m = un ? ((mx == NEG_INF) ? NEG_INF : mx) : m + d;
;     }
; #pragma unroll
;     for (int kt = 0; kt < 4; ++kt)
; #pragma unroll
;         for (int i = 0; i < 4; ++i) s[kt][i] = __builtin_amdgcn_exp2f(s[kt][i]);
; #pragma unroll
;     for (int j = 0; j < 2; ++j) { v4u w; w.x = cvtpk(s[2 * j][0], s[2 * j][1]); w.y = cvtpk(s[2 * j][2], s[2 * j][3]); w.z = cvtpk(s[2 * j + 1][0], s[2 * j + 1][1]); w.w = cvtpk(s[2 * j + 1][2], s[2 * j + 1][3]); pf[j] = __builtin_bit_cast(ab8, w); }
; }
; template <bool PV, bool WITHL>
; DEV void pv64(const LAS unsigned char* Vb, const AttnCtx& C, const ab8 (&pf)[2][2], f32x4 (&O)[2][4], f32x4 (&L)[2], bool a0, bool a1) {
;     if (PV) {
;         const int vr = 4 * C.q4 + (C.n >> 2), vc = (C.n & 3) >> 1, vs = 8 * (C.n & 1);
;         ab8 vf[4][2];
; #pragma unroll
;         for (int dt = 0; dt < 4; ++dt)
; #pragma unroll
.Lmy_fb_0:
	v_add3_u32 v236, s27, v199, v198
	v_add3_u32 v237, s27, v197, v198
	ds_read_b128 v[66:69], v236 offset:0
	ds_read_b128 v[70:73], v237 offset:0
	ds_read_b128 v[74:77], v236 offset:2048
	ds_read_b128 v[78:81], v237 offset:2048
	ds_read_b128 v[82:85], v236 offset:4096
	ds_read_b128 v[86:89], v237 offset:4096
	ds_read_b128 v[90:93], v236 offset:6144
	ds_read_b128 v[94:97], v237 offset:6144
	v_and_b32_e32 v243, s8, v206
	v_and_b32_e32 v244, s8, v207
	v_cmp_ne_u32_e64 s[10:11], 0, v243
	v_cmp_ne_u32_e64 s[14:15], 0, v244
	v_cmp_eq_f32_e64 s[12:13], s3, v213
	v_cmp_eq_f32_e64 s[16:17], s3, v212
	v_add_u32_e32 v238, s27, v200
	v_add3_u32 v239, v238, v201, v209
	v_add3_u32 v240, v238, v202, v209
	v_cndmask_b32_e64 v228, v213, 0, s[12:13]
	v_cndmask_b32_e64 v232, v212, 0, s[16:17]
	v_sub_f32_e32 v228, v175, v228
	v_sub_f32_e32 v232, v175, v232
	v_add3_u32 v241, v238, v203, v209
	v_add3_u32 v242, v238, v204, v209
	v_cndmask_b32_e64 v228, v173, v228, s[10:11]
	v_cndmask_b32_e64 v232, v173, v232, s[14:15]
	s_and_b64 s[12:13], s[10:11], s[12:13]
	s_and_b64 s[16:17], s[14:15], s[16:17]
	s_or_b64 s[12:13], s[12:13], s[16:17]
	v_mov_b32_e32 v229, v228
	v_mov_b32_e32 v230, v228
	v_mov_b32_e32 v231, v228
	v_mov_b32_e32 v233, v232
	v_mov_b32_e32 v234, v232
	v_mov_b32_e32 v235, v232
	s_waitcnt lgkmcnt(0)
	v_mfma_f32_16x16x32_bf16 v[98:101], v[66:69], v[10:13], v[232:235]
	v_mfma_f32_16x16x32_bf16 v[102:105], v[74:77], v[10:13], v[232:235]
	v_mfma_f32_16x16x32_bf16 v[106:109], v[82:85], v[10:13], v[232:235]
	v_mfma_f32_16x16x32_bf16 v[110:113], v[90:93], v[10:13], v[232:235]
	v_mfma_f32_16x16x32_bf16 v[66:69], v[66:69], v[2:5], v[228:231]
	v_mfma_f32_16x16x32_bf16 v[74:77], v[74:77], v[2:5], v[228:231]
	v_mfma_f32_16x16x32_bf16 v[82:85], v[82:85], v[2:5], v[228:231]
	v_mfma_f32_16x16x32_bf16 v[90:93], v[90:93], v[2:5], v[228:231]
	v_mfma_f32_16x16x32_bf16 v[66:69], v[70:73], v[6:9], v[66:69]
	v_mfma_f32_16x16x32_bf16 v[74:77], v[78:81], v[6:9], v[74:77]
	v_mfma_f32_16x16x32_bf16 v[82:85], v[86:89], v[6:9], v[82:85]
	v_mfma_f32_16x16x32_bf16 v[90:93], v[94:97], v[6:9], v[90:93]
	v_mfma_f32_16x16x32_bf16 v[70:73], v[70:73], v[14:17], v[98:101]
	v_mfma_f32_16x16x32_bf16 v[78:81], v[78:81], v[14:17], v[102:105]
	v_mfma_f32_16x16x32_bf16 v[86:89], v[86:89], v[14:17], v[106:109]
	v_mfma_f32_16x16x32_bf16 v[94:97], v[94:97], v[14:17], v[110:113]
	ds_read_b64_tr_b16 v[114:115], v241 offset:8192
	ds_read_b64_tr_b16 v[116:117], v241 offset:10240
	ds_read_b64_tr_b16 v[118:119], v241 offset:12288
	ds_read_b64_tr_b16 v[120:121], v241 offset:14336
	ds_read_b64_tr_b16 v[122:123], v242 offset:8192
	ds_read_b64_tr_b16 v[124:125], v242 offset:10240
	ds_read_b64_tr_b16 v[126:127], v242 offset:12288
	ds_read_b64_tr_b16 v[128:129], v242 offset:14336
	ds_read_b64_tr_b16 v[98:99], v239 offset:8192
	ds_read_b64_tr_b16 v[100:101], v239 offset:10240
	ds_read_b64_tr_b16 v[102:103], v239 offset:12288
	ds_read_b64_tr_b16 v[104:105], v239 offset:14336
	ds_read_b64_tr_b16 v[106:107], v240 offset:8192
	ds_read_b64_tr_b16 v[108:109], v240 offset:10240
	ds_read_b64_tr_b16 v[110:111], v240 offset:12288
	ds_read_b64_tr_b16 v[112:113], v240 offset:14336
	v_max3_f32 v243, v66, v67, v68
	v_max3_f32 v244, v69, v74, v75
	v_max3_f32 v245, v76, v77, v82
	v_max3_f32 v246, v83, v84, v85
	v_max3_f32 v243, v243, v244, v90
	v_max3_f32 v245, v245, v246, v91
	v_max3_f32 v243, v243, v92, v93
	v_max_f32_e32 v243, v243, v245
	v_cmp_lt_f32_e32 vcc, s96, v243
	s_or_b64 s[12:13], s[12:13], vcc
	v_max3_f32 v243, v70, v71, v72
	v_max3_f32 v244, v73, v78, v79
	v_max3_f32 v245, v80, v81, v86
	v_max3_f32 v246, v87, v88, v89
	v_max3_f32 v243, v243, v244, v94
	v_max3_f32 v245, v245, v246, v95
	v_max3_f32 v243, v243, v96, v97
	v_max_f32_e32 v243, v243, v245
	v_cmp_lt_f32_e32 vcc, s96, v243
	s_or_b64 s[12:13], s[12:13], vcc
	s_cmp_lg_u64 s[12:13], 0
	s_cbranch_scc1 .Lmy_slow_b_0
	v_exp_f32_e32 v66, v66
	v_exp_f32_e32 v67, v67
	v_exp_f32_e32 v68, v68
	v_exp_f32_e32 v69, v69
	v_exp_f32_e32 v74, v74
	v_exp_f32_e32 v75, v75
	v_exp_f32_e32 v76, v76
	v_exp_f32_e32 v77, v77
	v_exp_f32_e32 v82, v82
	v_exp_f32_e32 v83, v83
	v_exp_f32_e32 v84, v84
	v_exp_f32_e32 v85, v85
	v_exp_f32_e32 v90, v90
	v_exp_f32_e32 v91, v91
	v_exp_f32_e32 v92, v92
	v_exp_f32_e32 v93, v93
	v_exp_f32_e32 v70, v70
	v_exp_f32_e32 v71, v71
	v_exp_f32_e32 v72, v72
	v_exp_f32_e32 v73, v73
	v_exp_f32_e32 v78, v78
	v_exp_f32_e32 v79, v79
	v_exp_f32_e32 v80, v80
	v_exp_f32_e32 v81, v81
	v_exp_f32_e32 v86, v86
	v_exp_f32_e32 v87, v87
	v_exp_f32_e32 v88, v88
	v_exp_f32_e32 v89, v89
	v_exp_f32_e32 v94, v94
	v_exp_f32_e32 v95, v95
	v_exp_f32_e32 v96, v96
	v_exp_f32_e32 v97, v97
	v_cvt_pk_bf16_f32 v130, v66, v67
	v_cvt_pk_bf16_f32 v131, v68, v69
	v_cvt_pk_bf16_f32 v132, v74, v75
	v_cvt_pk_bf16_f32 v133, v76, v77
	v_cvt_pk_bf16_f32 v134, v82, v83
	v_cvt_pk_bf16_f32 v135, v84, v85
	v_cvt_pk_bf16_f32 v136, v90, v91
	v_cvt_pk_bf16_f32 v137, v92, v93
	v_cvt_pk_bf16_f32 v228, v70, v71
	v_cvt_pk_bf16_f32 v229, v72, v73
	v_cvt_pk_bf16_f32 v230, v78, v79
	v_cvt_pk_bf16_f32 v231, v80, v81
	v_cvt_pk_bf16_f32 v232, v86, v87
	v_cvt_pk_bf16_f32 v233, v88, v89
	v_cvt_pk_bf16_f32 v234, v94, v95
	v_cvt_pk_bf16_f32 v235, v96, v97
	s_nop 1
	s_waitcnt lgkmcnt(12)
	v_mfma_f32_16x16x32_bf16 v[50:53], v[114:117], v[130:133], v[50:53]
	v_mfma_f32_16x16x32_bf16 v[30:33], v[114:117], v[228:231], v[30:33]
	v_mfma_f32_16x16x32_bf16 v[58:61], v[22:25], v[130:133], v[58:61]
	v_mfma_f32_16x16x32_bf16 v[42:45], v[22:25], v[228:231], v[42:45]
	v_mfma_f32_16x16x32_bf16 v[50:53], v[118:121], v[134:137], v[50:53]
	v_mfma_f32_16x16x32_bf16 v[30:33], v[118:121], v[232:235], v[30:33]
	s_waitcnt lgkmcnt(8)
	v_mfma_f32_16x16x32_bf16 v[46:49], v[122:125], v[130:133], v[46:49]
	v_mfma_f32_16x16x32_bf16 v[26:29], v[122:125], v[228:231], v[26:29]
	v_mfma_f32_16x16x32_bf16 v[46:49], v[126:129], v[134:137], v[46:49]
	v_mfma_f32_16x16x32_bf16 v[26:29], v[126:129], v[232:235], v[26:29]
	s_waitcnt lgkmcnt(4)
	v_mfma_f32_16x16x32_bf16 v[62:65], v[98:101], v[130:133], v[62:65]
	v_mfma_f32_16x16x32_bf16 v[38:41], v[98:101], v[228:231], v[38:41]
	v_mfma_f32_16x16x32_bf16 v[58:61], v[22:25], v[134:137], v[58:61]
	v_mfma_f32_16x16x32_bf16 v[42:45], v[22:25], v[232:235], v[42:45]
	v_mfma_f32_16x16x32_bf16 v[62:65], v[102:105], v[134:137], v[62:65]
	v_mfma_f32_16x16x32_bf16 v[38:41], v[102:105], v[232:235], v[38:41]
	s_waitcnt lgkmcnt(0)
	v_mfma_f32_16x16x32_bf16 v[54:57], v[106:109], v[130:133], v[54:57]
	v_mfma_f32_16x16x32_bf16 v[34:37], v[106:109], v[228:231], v[34:37]
	v_mfma_f32_16x16x32_bf16 v[54:57], v[110:113], v[134:137], v[54:57]
	v_mfma_f32_16x16x32_bf16 v[34:37], v[110:113], v[232:235], v[34:37]
	s_nop 7
	s_branch .LBB0_1196

; #define LAS __attribute__((address_space(3)))
; DEV s16x4 vtr(const LAS unsigned char* p) { typedef short v4i16_t __attribute__((ext_vector_type(4))); return __builtin_bit_cast(s16x4, __builtin_amdgcn_ds_read_tr16_b64_v4i16((LAS v4i16_t*)p)); }
; DEV void ref_step(f32x4 (&s)[4], float& m, f32x4 (&O)[4], f32x4& L, ab8 (&pf)[2], bool colact) {
;     ...
; #pragma unroll
;     for (int kt = 0; kt < 4; ++kt)
; #pragma unroll
;         for (int i = 0; i < 4; ++i) s[kt][i] = __builtin_amdgcn_exp2f(s[kt][i]);
; #pragma unroll
;     for (int j = 0; j < 2; ++j) { v4u w; w.x = cvtpk(s[2 * j][0], s[2 * j][1]); w.y = cvtpk(s[2 * j][2], s[2 * j][3]); w.z = cvtpk(s[2 * j + 1][0], s[2 * j + 1][1]); w.w = cvtpk(s[2 * j + 1][2], s[2 * j + 1][3]); pf[j] = __builtin_bit_cast(ab8, w); }
; }
; template <bool PV, bool WITHL>
; DEV void pv64(const LAS unsigned char* Vb, const AttnCtx& C, const ab8 (&pf)[2][2], f32x4 (&O)[2][4], f32x4 (&L)[2], bool a0, bool a1) {
;     if (PV) {
;         const int vr = 4 * C.q4 + (C.n >> 2), vc = (C.n & 3) >> 1, vs = 8 * (C.n & 1);
;         ab8 vf[4][2];
; #pragma unroll
;         for (int dt = 0; dt < 4; ++dt)
; #pragma unroll
;             for (int j = 0; j < 2; ++j) {
;                 const s16x4 lo = vtr(Vb + swz(32 * j + vr, 2 * dt + vc) + vs), hi = vtr(Vb + swz(32 * j + 16 + vr, 2 * dt + vc) + vs);
;                 vf[dt][j] = __builtin_shufflevector(lo, hi, 0, 1, 2, 3, 4, 5, 6, 7); }
;         __builtin_amdgcn_sched_barrier(0);
; #pragma unroll
;         for (int dt = 0; dt < 4; ++dt)
; #pragma unroll
;             for (int j = 0; j < 2; ++j) {
;                 if (a0) O[0][dt] = __builtin_amdgcn_mfma_f32_16x16x32_bf16(vf[dt][j], pf[0][j], O[0][dt], 0, 0, 0);
;                 if (a1) O[1][dt] = __builtin_amdgcn_mfma_f32_16x16x32_bf16(vf[dt][j], pf[1][j], O[1][dt], 0, 0, 0); }
;     }
;     if (WITHL) {
;         const short one = (C.n == 0) ? (short)0x3F80 : (short)0; const ab8 ones = {one, one, one, one, one, one, one, one};
; #pragma unroll
;         for (int j = 0; j < 2; ++j) {
;             if (a0) L[0] = __builtin_amdgcn_mfma_f32_16x16x32_bf16(ones, pf[0][j], L[0], 0, 0, 0);
;             if (a1) L[1] = __builtin_amdgcn_mfma_f32_16x16x32_bf16(ones, pf[1][j], L[1], 0, 0, 0);
;         }
;     }
; }
.LBB0_1179:
	v_exp_f32_e32 v104, v104
	v_exp_f32_e32 v105, v105
	v_exp_f32_e32 v110, v110
	v_exp_f32_e32 v111, v111
	v_exp_f32_e32 v112, v112
	v_exp_f32_e32 v113, v113
	v_exp_f32_e32 v106, v106
	v_exp_f32_e32 v107, v107
	v_exp_f32_e32 v108, v108
	v_exp_f32_e32 v109, v109
	v_exp_f32_e32 v98, v98
	v_exp_f32_e32 v99, v99
	v_exp_f32_e32 v100, v100
	v_exp_f32_e32 v101, v101
	v_exp_f32_e32 v102, v102
	v_exp_f32_e32 v103, v103
	v_add_u32_e32 v215, s27, v200
	v_cvt_pk_bf16_f32 v137, v104, v105
	v_add3_u32 v104, v215, v201, v209
	v_add3_u32 v217, v215, v202, v209
	v_cvt_pk_bf16_f32 v110, v110, v111
	v_cvt_pk_bf16_f32 v111, v112, v113
	v_cvt_pk_bf16_f32 v112, v106, v107
	v_cvt_pk_bf16_f32 v113, v108, v109
	v_cvt_pk_bf16_f32 v134, v98, v99
	v_cvt_pk_bf16_f32 v135, v100, v101
	v_cvt_pk_bf16_f32 v136, v102, v103
	ds_read_b64_tr_b16 v[98:99], v104 offset:8192
	ds_read_b64_tr_b16 v[100:101], v104 offset:10240
	ds_read_b64_tr_b16 v[102:103], v104 offset:12288
	ds_read_b64_tr_b16 v[104:105], v104 offset:14336
	ds_read_b64_tr_b16 v[106:107], v217 offset:8192
	ds_read_b64_tr_b16 v[108:109], v217 offset:10240
	ds_read_b64_tr_b16 v[228:229], v217 offset:12288
	ds_read_b64_tr_b16 v[230:231], v217 offset:14336
	v_add3_u32 v217, v215, v203, v209
	v_add3_u32 v215, v215, v204, v209
	ds_read_b64_tr_b16 v[232:233], v217 offset:8192
	ds_read_b64_tr_b16 v[234:235], v217 offset:10240
	ds_read_b64_tr_b16 v[236:237], v217 offset:12288
	ds_read_b64_tr_b16 v[238:239], v217 offset:14336
	ds_read_b64_tr_b16 v[240:241], v215 offset:8192
	ds_read_b64_tr_b16 v[242:243], v215 offset:10240
	ds_read_b64_tr_b16 v[244:245], v215 offset:12288
	ds_read_b64_tr_b16 v[246:247], v215 offset:14336
	s_waitcnt lgkmcnt(14)
	v_mfma_f32_16x16x32_bf16 v[98:101], v[98:101], v[110:113], v[114:117]
	s_mov_b64 s[12:13], 0
	s_waitcnt lgkmcnt(12)
	v_mfma_f32_16x16x32_bf16 v[98:101], v[102:105], v[134:137], v[98:101]
	s_waitcnt lgkmcnt(10)
	v_mfma_f32_16x16x32_bf16 v[102:105], v[106:109], v[110:113], v[118:121]
	s_waitcnt lgkmcnt(6)
	v_mfma_f32_16x16x32_bf16 v[106:109], v[232:235], v[110:113], v[122:125]
	s_waitcnt lgkmcnt(2)
	v_mfma_f32_16x16x32_bf16 v[114:117], v[240:243], v[110:113], v[126:129]
	v_mfma_f32_16x16x32_bf16 v[110:113], v[22:25], v[110:113], v[130:133]
	v_mfma_f32_16x16x32_bf16 v[102:105], v[228:231], v[134:137], v[102:105]
	v_mfma_f32_16x16x32_bf16 v[106:109], v[236:239], v[134:137], v[106:109]
	s_waitcnt lgkmcnt(0)
	v_mfma_f32_16x16x32_bf16 v[118:121], v[244:247], v[134:137], v[114:117]
	v_mfma_f32_16x16x32_bf16 v[110:113], v[22:25], v[134:137], v[110:113]

; #define LAS __attribute__((address_space(3)))
; DEV s16x4 vtr(const LAS unsigned char* p) { typedef short v4i16_t __attribute__((ext_vector_type(4))); return __builtin_bit_cast(s16x4, __builtin_amdgcn_ds_read_tr16_b64_v4i16((LAS v4i16_t*)p)); }
; DEV void ref_step(f32x4 (&s)[4], float& m, f32x4 (&O)[4], f32x4& L, ab8 (&pf)[2], bool colact) {
;     ...
; #pragma unroll
;     for (int kt = 0; kt < 4; ++kt)
; #pragma unroll
;         for (int i = 0; i < 4; ++i) s[kt][i] = __builtin_amdgcn_exp2f(s[kt][i]);
; #pragma unroll
;     for (int j = 0; j < 2; ++j) { v4u w; w.x = cvtpk(s[2 * j][0], s[2 * j][1]); w.y = cvtpk(s[2 * j][2], s[2 * j][3]); w.z = cvtpk(s[2 * j + 1][0], s[2 * j + 1][1]); w.w = cvtpk(s[2 * j + 1][2], s[2 * j + 1][3]); pf[j] = __builtin_bit_cast(ab8, w); }
; }
; template <bool PV, bool WITHL>
; DEV void pv64(const LAS unsigned char* Vb, const AttnCtx& C, const ab8 (&pf)[2][2], f32x4 (&O)[2][4], f32x4 (&L)[2], bool a0, bool a1) {
;     if (PV) {
;         const int vr = 4 * C.q4 + (C.n >> 2), vc = (C.n & 3) >> 1, vs = 8 * (C.n & 1);
;         ab8 vf[4][2];
; #pragma unroll
;         for (int dt = 0; dt < 4; ++dt)
; #pragma unroll
;             for (int j = 0; j < 2; ++j) {
;                 const s16x4 lo = vtr(Vb + swz(32 * j + vr, 2 * dt + vc) + vs), hi = vtr(Vb + swz(32 * j + 16 + vr, 2 * dt + vc) + vs);
;                 vf[dt][j] = __builtin_shufflevector(lo, hi, 0, 1, 2, 3, 4, 5, 6, 7); }
;         __builtin_amdgcn_sched_barrier(0);
; #pragma unroll
;         for (int dt = 0; dt < 4; ++dt)
; #pragma unroll
;             for (int j = 0; j < 2; ++j) {
;                 if (a0) O[0][dt] = __builtin_amdgcn_mfma_f32_16x16x32_bf16(vf[dt][j], pf[0][j], O[0][dt], 0, 0, 0);
;                 if (a1) O[1][dt] = __builtin_amdgcn_mfma_f32_16x16x32_bf16(vf[dt][j], pf[1][j], O[1][dt], 0, 0, 0); }
;     }
;     if (WITHL) {
;         const short one = (C.n == 0) ? (short)0x3F80 : (short)0; const ab8 ones = {one, one, one, one, one, one, one, one};
; #pragma unroll
;         for (int j = 0; j < 2; ++j) {
;             if (a0) L[0] = __builtin_amdgcn_mfma_f32_16x16x32_bf16(ones, pf[0][j], L[0], 0, 0, 0);
;             if (a1) L[1] = __builtin_amdgcn_mfma_f32_16x16x32_bf16(ones, pf[1][j], L[1], 0, 0, 0);
;         }
;     }
; }
.LBB0_1185:
	v_exp_f32_e32 v92, v92
	v_exp_f32_e32 v93, v93
	v_exp_f32_e32 v90, v90
	v_exp_f32_e32 v91, v91
	v_exp_f32_e32 v74, v74
	v_exp_f32_e32 v75, v75
	v_exp_f32_e32 v76, v76
	v_exp_f32_e32 v77, v77
	v_exp_f32_e32 v70, v70
	v_exp_f32_e32 v71, v71
	v_exp_f32_e32 v72, v72
	v_exp_f32_e32 v73, v73
	v_exp_f32_e32 v102, v66
	v_exp_f32_e32 v103, v67
	v_exp_f32_e32 v104, v68
	v_exp_f32_e32 v105, v69
	v_add_u32_e32 v114, s27, v200
	v_cvt_pk_bf16_f32 v67, v92, v93
	v_add3_u32 v92, v114, v201, v209
	v_add3_u32 v108, v114, v202, v209
	v_add3_u32 v115, v114, v203, v209
	v_add3_u32 v114, v114, v204, v209
	v_cvt_pk_bf16_f32 v66, v90, v91
	v_cvt_pk_bf16_f32 v68, v74, v75
	v_cvt_pk_bf16_f32 v69, v76, v77
	v_cvt_pk_bf16_f32 v70, v70, v71
	v_cvt_pk_bf16_f32 v71, v72, v73
	v_cvt_pk_bf16_f32 v72, v102, v103
	v_cvt_pk_bf16_f32 v73, v104, v105
	ds_read_b64_tr_b16 v[74:75], v92 offset:8192
	ds_read_b64_tr_b16 v[76:77], v92 offset:10240
	ds_read_b64_tr_b16 v[90:91], v92 offset:12288
	ds_read_b64_tr_b16 v[92:93], v92 offset:14336
	ds_read_b64_tr_b16 v[102:103], v108 offset:8192
	ds_read_b64_tr_b16 v[104:105], v108 offset:10240
	ds_read_b64_tr_b16 v[106:107], v108 offset:12288
	ds_read_b64_tr_b16 v[108:109], v108 offset:14336
	ds_read_b64_tr_b16 v[110:111], v115 offset:8192
	ds_read_b64_tr_b16 v[112:113], v115 offset:10240
	ds_read_b64_tr_b16 v[118:119], v115 offset:12288
	ds_read_b64_tr_b16 v[120:121], v115 offset:14336
	ds_read_b64_tr_b16 v[130:131], v114 offset:8192
	ds_read_b64_tr_b16 v[132:133], v114 offset:10240
	ds_read_b64_tr_b16 v[134:135], v114 offset:12288
	ds_read_b64_tr_b16 v[136:137], v114 offset:14336
	s_waitcnt lgkmcnt(14)
	v_mfma_f32_16x16x32_bf16 v[74:77], v[74:77], v[66:69], v[78:81]
	v_mov_b32_e32 v216, v212
	s_mov_b64 s[12:13], 0
	s_waitcnt lgkmcnt(12)
	v_mfma_f32_16x16x32_bf16 v[114:117], v[90:93], v[70:73], v[74:77]
	s_waitcnt lgkmcnt(10)
	v_mfma_f32_16x16x32_bf16 v[74:77], v[102:105], v[66:69], v[82:85]
	v_mov_b64_e32 v[104:105], v[36:37]
	v_mov_b64_e32 v[102:103], v[34:35]
	s_waitcnt lgkmcnt(8)
	v_mfma_f32_16x16x32_bf16 v[122:125], v[106:109], v[70:73], v[74:77]
	v_mov_b64_e32 v[108:109], v[32:33]
	v_mov_b64_e32 v[106:107], v[30:31]
	s_waitcnt lgkmcnt(6)
	v_mfma_f32_16x16x32_bf16 v[74:77], v[110:113], v[66:69], v[86:89]
	v_mov_b64_e32 v[112:113], v[44:45]
	v_mov_b64_e32 v[110:111], v[42:43]
	s_waitcnt lgkmcnt(4)
	v_mfma_f32_16x16x32_bf16 v[126:129], v[118:121], v[70:73], v[74:77]
	v_mov_b64_e32 v[120:121], v[28:29]
	v_mov_b64_e32 v[118:119], v[26:27]
	s_waitcnt lgkmcnt(2)
	v_mfma_f32_16x16x32_bf16 v[74:77], v[130:133], v[66:69], v[94:97]
	v_mfma_f32_16x16x32_bf16 v[66:69], v[22:25], v[66:69], v[98:101]
	s_nop 2
	v_mov_b64_e32 v[100:101], v[40:41]
	s_waitcnt lgkmcnt(0)
	v_mfma_f32_16x16x32_bf16 v[130:133], v[134:137], v[70:73], v[74:77]
	v_mov_b64_e32 v[98:99], v[38:39]
	v_mfma_f32_16x16x32_bf16 v[134:137], v[22:25], v[70:73], v[66:69]

; #define LAS __attribute__((address_space(3)))
; DEV s16x4 vtr(const LAS unsigned char* p) { typedef short v4i16_t __attribute__((ext_vector_type(4))); return __builtin_bit_cast(s16x4, __builtin_amdgcn_ds_read_tr16_b64_v4i16((LAS v4i16_t*)p)); }
; DEV void ref_step(f32x4 (&s)[4], float& m, f32x4 (&O)[4], f32x4& L, ab8 (&pf)[2], bool colact) {
;     ...
; #pragma unroll
;     for (int kt = 0; kt < 4; ++kt)
; #pragma unroll
;         for (int i = 0; i < 4; ++i) s[kt][i] = __builtin_amdgcn_exp2f(s[kt][i]);
; #pragma unroll
;     for (int j = 0; j < 2; ++j) { v4u w; w.x = cvtpk(s[2 * j][0], s[2 * j][1]); w.y = cvtpk(s[2 * j][2], s[2 * j][3]); w.z = cvtpk(s[2 * j + 1][0], s[2 * j + 1][1]); w.w = cvtpk(s[2 * j + 1][2], s[2 * j + 1][3]); pf[j] = __builtin_bit_cast(ab8, w); }
; }
; template <bool PV, bool WITHL>
; DEV void pv64(const LAS unsigned char* Vb, const AttnCtx& C, const ab8 (&pf)[2][2], f32x4 (&O)[2][4], f32x4 (&L)[2], bool a0, bool a1) {
;     if (PV) {
;         const int vr = 4 * C.q4 + (C.n >> 2), vc = (C.n & 3) >> 1, vs = 8 * (C.n & 1);
;         ab8 vf[4][2];
; #pragma unroll
;         for (int dt = 0; dt < 4; ++dt)
; #pragma unroll
;             for (int j = 0; j < 2; ++j) {
;                 const s16x4 lo = vtr(Vb + swz(32 * j + vr, 2 * dt + vc) + vs), hi = vtr(Vb + swz(32 * j + 16 + vr, 2 * dt + vc) + vs);
;                 vf[dt][j] = __builtin_shufflevector(lo, hi, 0, 1, 2, 3, 4, 5, 6, 7); }
;         __builtin_amdgcn_sched_barrier(0);
; #pragma unroll
;         for (int dt = 0; dt < 4; ++dt)
; #pragma unroll
;             for (int j = 0; j < 2; ++j) {
;                 if (a0) O[0][dt] = __builtin_amdgcn_mfma_f32_16x16x32_bf16(vf[dt][j], pf[0][j], O[0][dt], 0, 0, 0);
;                 if (a1) O[1][dt] = __builtin_amdgcn_mfma_f32_16x16x32_bf16(vf[dt][j], pf[1][j], O[1][dt], 0, 0, 0); }
;     }
;     if (WITHL) {
;         const short one = (C.n == 0) ? (short)0x3F80 : (short)0; const ab8 ones = {one, one, one, one, one, one, one, one};
; #pragma unroll
;         for (int j = 0; j < 2; ++j) {
;             if (a0) L[0] = __builtin_amdgcn_mfma_f32_16x16x32_bf16(ones, pf[0][j], L[0], 0, 0, 0);
;             if (a1) L[1] = __builtin_amdgcn_mfma_f32_16x16x32_bf16(ones, pf[1][j], L[1], 0, 0, 0);
;         }
;     }
; }
.LBB0_1194:
	v_exp_f32_e32 v82, v82
	v_exp_f32_e32 v83, v83
	v_exp_f32_e32 v84, v84
	v_exp_f32_e32 v85, v85
	v_exp_f32_e32 v88, v88
	v_exp_f32_e32 v89, v89
	v_exp_f32_e32 v96, v96
	v_exp_f32_e32 v97, v97
	v_exp_f32_e32 v66, v66
	v_exp_f32_e32 v67, v67
	v_exp_f32_e32 v68, v68
	v_exp_f32_e32 v69, v69
	v_exp_f32_e32 v72, v72
	v_exp_f32_e32 v73, v73
	v_exp_f32_e32 v80, v80
	v_exp_f32_e32 v81, v81
	v_exp_f32_e32 v86, v86
	v_exp_f32_e32 v87, v87
	v_exp_f32_e32 v90, v90
	v_exp_f32_e32 v91, v91
	v_exp_f32_e32 v92, v92
	v_exp_f32_e32 v93, v93
	v_exp_f32_e32 v94, v94
	v_exp_f32_e32 v95, v95
	v_exp_f32_e32 v70, v70
	v_exp_f32_e32 v71, v71
	v_exp_f32_e32 v74, v74
	v_exp_f32_e32 v75, v75
	v_exp_f32_e32 v76, v76
	v_exp_f32_e32 v77, v77
	v_exp_f32_e32 v78, v78
	v_exp_f32_e32 v79, v79
	v_add_u32_e32 v98, s27, v200
	v_cvt_pk_bf16_f32 v82, v82, v83
	v_cvt_pk_bf16_f32 v83, v84, v85
	v_cvt_pk_bf16_f32 v85, v88, v89
	v_cvt_pk_bf16_f32 v89, v96, v97
	v_cvt_pk_bf16_f32 v66, v66, v67
	v_cvt_pk_bf16_f32 v67, v68, v69
	v_cvt_pk_bf16_f32 v69, v72, v73
	v_cvt_pk_bf16_f32 v73, v80, v81
	v_add3_u32 v80, v98, v201, v209
	v_add3_u32 v96, v98, v202, v209
	v_add3_u32 v99, v98, v203, v209
	v_add3_u32 v98, v98, v204, v209
	v_cvt_pk_bf16_f32 v84, v86, v87
	v_cvt_pk_bf16_f32 v86, v90, v91
	v_cvt_pk_bf16_f32 v87, v92, v93
	v_cvt_pk_bf16_f32 v88, v94, v95
	v_cvt_pk_bf16_f32 v68, v70, v71
	v_cvt_pk_bf16_f32 v70, v74, v75
	v_cvt_pk_bf16_f32 v71, v76, v77
	v_cvt_pk_bf16_f32 v72, v78, v79
	ds_read_b64_tr_b16 v[74:75], v80 offset:8192
	ds_read_b64_tr_b16 v[76:77], v80 offset:10240
	ds_read_b64_tr_b16 v[78:79], v80 offset:12288
	ds_read_b64_tr_b16 v[80:81], v80 offset:14336
	ds_read_b64_tr_b16 v[90:91], v96 offset:8192
	ds_read_b64_tr_b16 v[92:93], v96 offset:10240
	ds_read_b64_tr_b16 v[94:95], v96 offset:12288
	ds_read_b64_tr_b16 v[96:97], v96 offset:14336
	ds_read_b64_tr_b16 v[106:107], v99 offset:8192
	ds_read_b64_tr_b16 v[108:109], v99 offset:10240
	ds_read_b64_tr_b16 v[110:111], v99 offset:12288
	ds_read_b64_tr_b16 v[112:113], v99 offset:14336
	ds_read_b64_tr_b16 v[118:119], v98 offset:8192
	ds_read_b64_tr_b16 v[120:121], v98 offset:10240
	ds_read_b64_tr_b16 v[134:135], v98 offset:12288
	ds_read_b64_tr_b16 v[136:137], v98 offset:14336
	s_waitcnt lgkmcnt(10)
	v_mfma_f32_16x16x32_bf16 v[34:37], v[90:93], v[66:69], v[34:37]
	v_mov_b32_e32 v216, v212
	s_waitcnt lgkmcnt(6)
	v_mfma_f32_16x16x32_bf16 v[30:33], v[106:109], v[66:69], v[30:33]
	v_mfma_f32_16x16x32_bf16 v[38:41], v[74:77], v[66:69], v[38:41]
	v_mfma_f32_16x16x32_bf16 v[102:105], v[94:97], v[70:73], v[34:37]
	v_mfma_f32_16x16x32_bf16 v[34:37], v[106:109], v[82:85], v[50:53]
	s_waitcnt lgkmcnt(4)
	v_mfma_f32_16x16x32_bf16 v[106:109], v[110:113], v[70:73], v[30:33]
	s_waitcnt lgkmcnt(2)
	v_mfma_f32_16x16x32_bf16 v[30:33], v[118:121], v[82:85], v[46:49]
	v_mfma_f32_16x16x32_bf16 v[26:29], v[118:121], v[66:69], v[26:29]
	v_mfma_f32_16x16x32_bf16 v[62:65], v[74:77], v[82:85], v[62:65]
	v_mfma_f32_16x16x32_bf16 v[98:101], v[78:81], v[70:73], v[38:41]
	v_mfma_f32_16x16x32_bf16 v[38:41], v[90:93], v[82:85], v[54:57]
	s_waitcnt lgkmcnt(0)
	v_mfma_f32_16x16x32_bf16 v[130:133], v[134:137], v[86:89], v[30:33]
	v_mfma_f32_16x16x32_bf16 v[118:121], v[134:137], v[70:73], v[26:29]
	v_mfma_f32_16x16x32_bf16 v[26:29], v[22:25], v[82:85], v[58:61]
	v_mfma_f32_16x16x32_bf16 v[30:33], v[22:25], v[66:69], v[42:45]
	v_mfma_f32_16x16x32_bf16 v[114:117], v[78:81], v[86:89], v[62:65]
	v_mfma_f32_16x16x32_bf16 v[122:125], v[94:97], v[86:89], v[38:41]
	v_mfma_f32_16x16x32_bf16 v[126:129], v[110:113], v[86:89], v[34:37]
	v_mfma_f32_16x16x32_bf16 v[134:137], v[22:25], v[86:89], v[26:29]
	v_mfma_f32_16x16x32_bf16 v[110:113], v[22:25], v[70:73], v[30:33]

; DEV void qk64(const LAS unsigned char* Kb, const AttnCtx& C, const ab8 (&qf)[2][2], f32x4 (&s)[2][4], float init0, float init1, bool a0, bool a1) {
;     ab8 k0[4], k1[4];
; #pragma unroll
;     for (int kt = 0; kt < 4; ++kt) { k0[kt] = *(const LAS ab8*)(Kb + swz(16 * kt + C.n, C.q4)); k1[kt] = *(const LAS ab8*)(Kb + swz(16 * kt + C.n, 4 + C.q4)); }
;     __builtin_amdgcn_sched_barrier(0);
; #pragma unroll
;     for (int kt = 0; kt < 4; ++kt) {
;         if (a0) { f32x4 c = {init0, init0, init0, init0}; c = __builtin_amdgcn_mfma_f32_16x16x32_bf16(k0[kt], qf[0][0], c, 0, 0, 0); s[0][kt] = __builtin_amdgcn_mfma_f32_16x16x32_bf16(k1[kt], qf[0][1], c, 0, 0, 0); }
;         if (a1) { f32x4 c = {init1, init1, init1, init1}; c = __builtin_amdgcn_mfma_f32_16x16x32_bf16(k0[kt], qf[1][0], c, 0, 0, 0); s[1][kt] = __builtin_amdgcn_mfma_f32_16x16x32_bf16(k1[kt], qf[1][1], c, 0, 0, 0); }
; DEV void ref_step(f32x4 (&s)[4], float& m, f32x4 (&O)[4], f32x4& L, ab8 (&pf)[2], bool colact) {
;     ...
;     const bool slow = (colact && m == NEG_INF) || mx > 64.f;
;     if (__any(slow)) {
;         mx = fmaxf(mx, __shfl_xor(mx, 16)); mx = fmaxf(mx, __shfl_xor(mx, 32));
;         const bool un = (m == NEG_INF);
;         const float d = (mx == NEG_INF) ? 0.f : (un ? mx : fmaxf(mx, 0.f));
;         const float sc = un ? 1.f : __builtin_amdgcn_exp2f(-d);
; #pragma unroll
;         for (int kt = 0; kt < 4; ++kt) s[kt] = s[kt] - d;
; #pragma unroll
;         for (int dt = 0; dt < 4; ++dt) O[dt] = O[dt] * sc;
;         L = L * sc;
;         m = un ? ((mx == NEG_INF) ? NEG_INF : mx) : m + d;
;     }
; #pragma unroll
;     for (int kt = 0; kt < 4; ++kt)
; #pragma unroll
;         for (int i = 0; i < 4; ++i) s[kt][i] = __builtin_amdgcn_exp2f(s[kt][i]);
; #pragma unroll
;     for (int j = 0; j < 2; ++j) { v4u w; w.x = cvtpk(s[2 * j][0], s[2 * j][1]); w.y = cvtpk(s[2 * j][2], s[2 * j][3]); w.z = cvtpk(s[2 * j + 1][0], s[2 * j + 1][1]); w.w = cvtpk(s[2 * j + 1][2], s[2 * j + 1][3]); pf[j] = __builtin_bit_cast(ab8, w); }
; }
; template <bool PV, bool WITHL>
; DEV void pv64(const LAS unsigned char* Vb, const AttnCtx& C, const ab8 (&pf)[2][2], f32x4 (&O)[2][4], f32x4 (&L)[2], bool a0, bool a1) {
;     if (PV) {
;         const int vr = 4 * C.q4 + (C.n >> 2), vc = (C.n & 3) >> 1, vs = 8 * (C.n & 1);
;         ab8 vf[4][2];
; #pragma unroll
;         for (int dt = 0; dt < 4; ++dt)
; #pragma unroll
.Lmy_fb_1:
	v_add3_u32 v236, s27, v199, v198
	v_add3_u32 v237, s27, v197, v198
	ds_read_b128 v[66:69], v236 offset:16384
	ds_read_b128 v[70:73], v237 offset:16384
	ds_read_b128 v[74:77], v236 offset:18432
	ds_read_b128 v[78:81], v237 offset:18432
	ds_read_b128 v[82:85], v236 offset:20480
	ds_read_b128 v[86:89], v237 offset:20480
	ds_read_b128 v[90:93], v236 offset:22528
	ds_read_b128 v[94:97], v237 offset:22528
	v_and_b32_e32 v243, s8, v206
	v_and_b32_e32 v244, s8, v207
	v_cmp_ne_u32_e64 s[10:11], 0, v243
	v_cmp_ne_u32_e64 s[14:15], 0, v244
	v_cmp_eq_f32_e64 s[12:13], s3, v213
	v_cmp_eq_f32_e64 s[16:17], s3, v212
	v_add_u32_e32 v238, s27, v200
	v_add3_u32 v239, v238, v201, v209
	v_add3_u32 v240, v238, v202, v209
	v_cndmask_b32_e64 v228, v213, 0, s[12:13]
	v_cndmask_b32_e64 v232, v212, 0, s[16:17]
	v_sub_f32_e32 v228, v175, v228
	v_sub_f32_e32 v232, v175, v232
	v_add3_u32 v241, v238, v203, v209
	v_add3_u32 v242, v238, v204, v209
	v_cndmask_b32_e64 v228, v173, v228, s[10:11]
	v_cndmask_b32_e64 v232, v173, v232, s[14:15]
	s_and_b64 s[12:13], s[10:11], s[12:13]
	s_and_b64 s[16:17], s[14:15], s[16:17]
	s_or_b64 s[12:13], s[12:13], s[16:17]
	v_mov_b32_e32 v229, v228
	v_mov_b32_e32 v230, v228
	v_mov_b32_e32 v231, v228
	v_mov_b32_e32 v233, v232
	v_mov_b32_e32 v234, v232
	v_mov_b32_e32 v235, v232
	s_waitcnt lgkmcnt(0)
	v_mfma_f32_16x16x32_bf16 v[98:101], v[66:69], v[10:13], v[232:235]
	v_mfma_f32_16x16x32_bf16 v[102:105], v[74:77], v[10:13], v[232:235]
	v_mfma_f32_16x16x32_bf16 v[106:109], v[82:85], v[10:13], v[232:235]
	v_mfma_f32_16x16x32_bf16 v[110:113], v[90:93], v[10:13], v[232:235]
	v_mfma_f32_16x16x32_bf16 v[66:69], v[66:69], v[2:5], v[228:231]
	v_mfma_f32_16x16x32_bf16 v[74:77], v[74:77], v[2:5], v[228:231]
	v_mfma_f32_16x16x32_bf16 v[82:85], v[82:85], v[2:5], v[228:231]
	v_mfma_f32_16x16x32_bf16 v[90:93], v[90:93], v[2:5], v[228:231]
	v_mfma_f32_16x16x32_bf16 v[66:69], v[70:73], v[6:9], v[66:69]
	v_mfma_f32_16x16x32_bf16 v[74:77], v[78:81], v[6:9], v[74:77]
	v_mfma_f32_16x16x32_bf16 v[82:85], v[86:89], v[6:9], v[82:85]
	v_mfma_f32_16x16x32_bf16 v[90:93], v[94:97], v[6:9], v[90:93]
	v_mfma_f32_16x16x32_bf16 v[70:73], v[70:73], v[14:17], v[98:101]
	v_mfma_f32_16x16x32_bf16 v[78:81], v[78:81], v[14:17], v[102:105]
	v_mfma_f32_16x16x32_bf16 v[86:89], v[86:89], v[14:17], v[106:109]
	v_mfma_f32_16x16x32_bf16 v[94:97], v[94:97], v[14:17], v[110:113]
	ds_read_b64_tr_b16 v[114:115], v241 offset:24576
	ds_read_b64_tr_b16 v[116:117], v241 offset:26624
	ds_read_b64_tr_b16 v[118:119], v241 offset:28672
	ds_read_b64_tr_b16 v[120:121], v241 offset:30720
	ds_read_b64_tr_b16 v[122:123], v242 offset:24576
	ds_read_b64_tr_b16 v[124:125], v242 offset:26624
	ds_read_b64_tr_b16 v[126:127], v242 offset:28672
	ds_read_b64_tr_b16 v[128:129], v242 offset:30720
	ds_read_b64_tr_b16 v[98:99], v239 offset:24576
	ds_read_b64_tr_b16 v[100:101], v239 offset:26624
	ds_read_b64_tr_b16 v[102:103], v239 offset:28672
	ds_read_b64_tr_b16 v[104:105], v239 offset:30720
	ds_read_b64_tr_b16 v[106:107], v240 offset:24576
	ds_read_b64_tr_b16 v[108:109], v240 offset:26624
	ds_read_b64_tr_b16 v[110:111], v240 offset:28672
	ds_read_b64_tr_b16 v[112:113], v240 offset:30720
	v_max3_f32 v243, v66, v67, v68
	v_max3_f32 v244, v69, v74, v75
	v_max3_f32 v245, v76, v77, v82
	v_max3_f32 v246, v83, v84, v85
	v_max3_f32 v243, v243, v244, v90
	v_max3_f32 v245, v245, v246, v91
	v_max3_f32 v243, v243, v92, v93
	v_max_f32_e32 v243, v243, v245
	v_cmp_lt_f32_e32 vcc, s96, v243
	s_or_b64 s[12:13], s[12:13], vcc
	v_max3_f32 v243, v70, v71, v72
	v_max3_f32 v244, v73, v78, v79
	v_max3_f32 v245, v80, v81, v86
	v_max3_f32 v246, v87, v88, v89
	v_max3_f32 v243, v243, v244, v94
	v_max3_f32 v245, v245, v246, v95
	v_max3_f32 v243, v243, v96, v97
	v_max_f32_e32 v243, v243, v245
	v_cmp_lt_f32_e32 vcc, s96, v243
	s_or_b64 s[12:13], s[12:13], vcc
	s_cmp_lg_u64 s[12:13], 0
	s_cbranch_scc1 .Lmy_slow_b_1
	v_exp_f32_e32 v66, v66
	v_exp_f32_e32 v67, v67
	v_exp_f32_e32 v68, v68
	v_exp_f32_e32 v69, v69
	v_exp_f32_e32 v74, v74
	v_exp_f32_e32 v75, v75
	v_exp_f32_e32 v76, v76
	v_exp_f32_e32 v77, v77
	v_exp_f32_e32 v82, v82
	v_exp_f32_e32 v83, v83
	v_exp_f32_e32 v84, v84
	v_exp_f32_e32 v85, v85
	v_exp_f32_e32 v90, v90
	v_exp_f32_e32 v91, v91
	v_exp_f32_e32 v92, v92
	v_exp_f32_e32 v93, v93
	v_exp_f32_e32 v70, v70
	v_exp_f32_e32 v71, v71
	v_exp_f32_e32 v72, v72
	v_exp_f32_e32 v73, v73
	v_exp_f32_e32 v78, v78
	v_exp_f32_e32 v79, v79
	v_exp_f32_e32 v80, v80
	v_exp_f32_e32 v81, v81
	v_exp_f32_e32 v86, v86
	v_exp_f32_e32 v87, v87
	v_exp_f32_e32 v88, v88
	v_exp_f32_e32 v89, v89
	v_exp_f32_e32 v94, v94
	v_exp_f32_e32 v95, v95
	v_exp_f32_e32 v96, v96
	v_exp_f32_e32 v97, v97
	v_cvt_pk_bf16_f32 v130, v66, v67
	v_cvt_pk_bf16_f32 v131, v68, v69
	v_cvt_pk_bf16_f32 v132, v74, v75
	v_cvt_pk_bf16_f32 v133, v76, v77
	v_cvt_pk_bf16_f32 v134, v82, v83
	v_cvt_pk_bf16_f32 v135, v84, v85
	v_cvt_pk_bf16_f32 v136, v90, v91
	v_cvt_pk_bf16_f32 v137, v92, v93
	v_cvt_pk_bf16_f32 v228, v70, v71
	v_cvt_pk_bf16_f32 v229, v72, v73
	v_cvt_pk_bf16_f32 v230, v78, v79
	v_cvt_pk_bf16_f32 v231, v80, v81
	v_cvt_pk_bf16_f32 v232, v86, v87
	v_cvt_pk_bf16_f32 v233, v88, v89
	v_cvt_pk_bf16_f32 v234, v94, v95
	v_cvt_pk_bf16_f32 v235, v96, v97
	s_nop 1
	s_waitcnt lgkmcnt(12)
	v_mfma_f32_16x16x32_bf16 v[50:53], v[114:117], v[130:133], v[50:53]
	v_mfma_f32_16x16x32_bf16 v[30:33], v[114:117], v[228:231], v[30:33]
	v_mfma_f32_16x16x32_bf16 v[58:61], v[22:25], v[130:133], v[58:61]
	v_mfma_f32_16x16x32_bf16 v[42:45], v[22:25], v[228:231], v[42:45]
	v_mfma_f32_16x16x32_bf16 v[50:53], v[118:121], v[134:137], v[50:53]
	v_mfma_f32_16x16x32_bf16 v[30:33], v[118:121], v[232:235], v[30:33]
	s_waitcnt lgkmcnt(8)
	v_mfma_f32_16x16x32_bf16 v[46:49], v[122:125], v[130:133], v[46:49]
	v_mfma_f32_16x16x32_bf16 v[26:29], v[122:125], v[228:231], v[26:29]
	v_mfma_f32_16x16x32_bf16 v[46:49], v[126:129], v[134:137], v[46:49]
	v_mfma_f32_16x16x32_bf16 v[26:29], v[126:129], v[232:235], v[26:29]
	s_waitcnt lgkmcnt(4)
	v_mfma_f32_16x16x32_bf16 v[62:65], v[98:101], v[130:133], v[62:65]
	v_mfma_f32_16x16x32_bf16 v[38:41], v[98:101], v[228:231], v[38:41]
	v_mfma_f32_16x16x32_bf16 v[58:61], v[22:25], v[134:137], v[58:61]
	v_mfma_f32_16x16x32_bf16 v[42:45], v[22:25], v[232:235], v[42:45]
	v_mfma_f32_16x16x32_bf16 v[62:65], v[102:105], v[134:137], v[62:65]
	v_mfma_f32_16x16x32_bf16 v[38:41], v[102:105], v[232:235], v[38:41]
	s_waitcnt lgkmcnt(0)
	v_mfma_f32_16x16x32_bf16 v[54:57], v[106:109], v[130:133], v[54:57]
	v_mfma_f32_16x16x32_bf16 v[34:37], v[106:109], v[228:231], v[34:37]
	v_mfma_f32_16x16x32_bf16 v[54:57], v[110:113], v[134:137], v[54:57]
	v_mfma_f32_16x16x32_bf16 v[34:37], v[110:113], v[232:235], v[34:37]
	s_nop 7
	s_branch .LBB0_1222

; #define LAS __attribute__((address_space(3)))
; DEV s16x4 vtr(const LAS unsigned char* p) { typedef short v4i16_t __attribute__((ext_vector_type(4))); return __builtin_bit_cast(s16x4, __builtin_amdgcn_ds_read_tr16_b64_v4i16((LAS v4i16_t*)p)); }
; DEV void ref_step(f32x4 (&s)[4], float& m, f32x4 (&O)[4], f32x4& L, ab8 (&pf)[2], bool colact) {
;     ...
; #pragma unroll
;     for (int kt = 0; kt < 4; ++kt)
; #pragma unroll
;         for (int i = 0; i < 4; ++i) s[kt][i] = __builtin_amdgcn_exp2f(s[kt][i]);
; #pragma unroll
;     for (int j = 0; j < 2; ++j) { v4u w; w.x = cvtpk(s[2 * j][0], s[2 * j][1]); w.y = cvtpk(s[2 * j][2], s[2 * j][3]); w.z = cvtpk(s[2 * j + 1][0], s[2 * j + 1][1]); w.w = cvtpk(s[2 * j + 1][2], s[2 * j + 1][3]); pf[j] = __builtin_bit_cast(ab8, w); }
; }
; template <bool PV, bool WITHL>
; DEV void pv64(const LAS unsigned char* Vb, const AttnCtx& C, const ab8 (&pf)[2][2], f32x4 (&O)[2][4], f32x4 (&L)[2], bool a0, bool a1) {
;     if (PV) {
;         const int vr = 4 * C.q4 + (C.n >> 2), vc = (C.n & 3) >> 1, vs = 8 * (C.n & 1);
;         ab8 vf[4][2];
; #pragma unroll
;         for (int dt = 0; dt < 4; ++dt)
; #pragma unroll
;             for (int j = 0; j < 2; ++j) {
;                 const s16x4 lo = vtr(Vb + swz(32 * j + vr, 2 * dt + vc) + vs), hi = vtr(Vb + swz(32 * j + 16 + vr, 2 * dt + vc) + vs);
;                 vf[dt][j] = __builtin_shufflevector(lo, hi, 0, 1, 2, 3, 4, 5, 6, 7); }
;         __builtin_amdgcn_sched_barrier(0);
; #pragma unroll
;         for (int dt = 0; dt < 4; ++dt)
; #pragma unroll
;             for (int j = 0; j < 2; ++j) {
;                 if (a0) O[0][dt] = __builtin_amdgcn_mfma_f32_16x16x32_bf16(vf[dt][j], pf[0][j], O[0][dt], 0, 0, 0);
;                 if (a1) O[1][dt] = __builtin_amdgcn_mfma_f32_16x16x32_bf16(vf[dt][j], pf[1][j], O[1][dt], 0, 0, 0); }
;     }
;     if (WITHL) {
;         const short one = (C.n == 0) ? (short)0x3F80 : (short)0; const ab8 ones = {one, one, one, one, one, one, one, one};
; #pragma unroll
;         for (int j = 0; j < 2; ++j) {
;             if (a0) L[0] = __builtin_amdgcn_mfma_f32_16x16x32_bf16(ones, pf[0][j], L[0], 0, 0, 0);
;             if (a1) L[1] = __builtin_amdgcn_mfma_f32_16x16x32_bf16(ones, pf[1][j], L[1], 0, 0, 0);
;         }
;     }
; }
.LBB0_1204:
	v_exp_f32_e32 v104, v104
	v_exp_f32_e32 v105, v105
	v_exp_f32_e32 v110, v110
	v_exp_f32_e32 v111, v111
	v_exp_f32_e32 v112, v112
	v_exp_f32_e32 v113, v113
	v_exp_f32_e32 v106, v106
	v_exp_f32_e32 v107, v107
	v_exp_f32_e32 v108, v108
	v_exp_f32_e32 v109, v109
	v_exp_f32_e32 v98, v98
	v_exp_f32_e32 v99, v99
	v_exp_f32_e32 v100, v100
	v_exp_f32_e32 v101, v101
	v_exp_f32_e32 v102, v102
	v_exp_f32_e32 v103, v103
	v_add_u32_e32 v215, s27, v200
	v_cvt_pk_bf16_f32 v137, v104, v105
	v_add3_u32 v104, v215, v201, v209
	v_add3_u32 v217, v215, v202, v209
	v_cvt_pk_bf16_f32 v110, v110, v111
	v_cvt_pk_bf16_f32 v111, v112, v113
	v_cvt_pk_bf16_f32 v112, v106, v107
	v_cvt_pk_bf16_f32 v113, v108, v109
	v_cvt_pk_bf16_f32 v134, v98, v99
	v_cvt_pk_bf16_f32 v135, v100, v101
	v_cvt_pk_bf16_f32 v136, v102, v103
	ds_read_b64_tr_b16 v[98:99], v104 offset:24576
	ds_read_b64_tr_b16 v[100:101], v104 offset:26624
	ds_read_b64_tr_b16 v[102:103], v104 offset:28672
	ds_read_b64_tr_b16 v[104:105], v104 offset:30720
	ds_read_b64_tr_b16 v[106:107], v217 offset:24576
	ds_read_b64_tr_b16 v[108:109], v217 offset:26624
	ds_read_b64_tr_b16 v[228:229], v217 offset:28672
	ds_read_b64_tr_b16 v[230:231], v217 offset:30720
	v_add3_u32 v217, v215, v203, v209
	v_add3_u32 v215, v215, v204, v209
	ds_read_b64_tr_b16 v[232:233], v217 offset:24576
	ds_read_b64_tr_b16 v[234:235], v217 offset:26624
	ds_read_b64_tr_b16 v[236:237], v217 offset:28672
	ds_read_b64_tr_b16 v[238:239], v217 offset:30720
	ds_read_b64_tr_b16 v[240:241], v215 offset:24576
	ds_read_b64_tr_b16 v[242:243], v215 offset:26624
	ds_read_b64_tr_b16 v[244:245], v215 offset:28672
	ds_read_b64_tr_b16 v[246:247], v215 offset:30720
	s_waitcnt lgkmcnt(14)
	v_mfma_f32_16x16x32_bf16 v[98:101], v[98:101], v[110:113], v[114:117]
	s_mov_b64 s[12:13], 0
	s_waitcnt lgkmcnt(12)
	v_mfma_f32_16x16x32_bf16 v[98:101], v[102:105], v[134:137], v[98:101]
	s_waitcnt lgkmcnt(10)
	v_mfma_f32_16x16x32_bf16 v[102:105], v[106:109], v[110:113], v[118:121]
	s_waitcnt lgkmcnt(6)
	v_mfma_f32_16x16x32_bf16 v[106:109], v[232:235], v[110:113], v[122:125]
	s_waitcnt lgkmcnt(2)
	v_mfma_f32_16x16x32_bf16 v[114:117], v[240:243], v[110:113], v[126:129]
	v_mfma_f32_16x16x32_bf16 v[110:113], v[22:25], v[110:113], v[130:133]
	v_mfma_f32_16x16x32_bf16 v[102:105], v[228:231], v[134:137], v[102:105]
	v_mfma_f32_16x16x32_bf16 v[106:109], v[236:239], v[134:137], v[106:109]
	s_waitcnt lgkmcnt(0)
	v_mfma_f32_16x16x32_bf16 v[118:121], v[244:247], v[134:137], v[114:117]
	v_mfma_f32_16x16x32_bf16 v[114:117], v[22:25], v[134:137], v[110:113]

; #define LAS __attribute__((address_space(3)))
; DEV s16x4 vtr(const LAS unsigned char* p) { typedef short v4i16_t __attribute__((ext_vector_type(4))); return __builtin_bit_cast(s16x4, __builtin_amdgcn_ds_read_tr16_b64_v4i16((LAS v4i16_t*)p)); }
; DEV void ref_step(f32x4 (&s)[4], float& m, f32x4 (&O)[4], f32x4& L, ab8 (&pf)[2], bool colact) {
;     ...
; #pragma unroll
;     for (int kt = 0; kt < 4; ++kt)
; #pragma unroll
;         for (int i = 0; i < 4; ++i) s[kt][i] = __builtin_amdgcn_exp2f(s[kt][i]);
; #pragma unroll
;     for (int j = 0; j < 2; ++j) { v4u w; w.x = cvtpk(s[2 * j][0], s[2 * j][1]); w.y = cvtpk(s[2 * j][2], s[2 * j][3]); w.z = cvtpk(s[2 * j + 1][0], s[2 * j + 1][1]); w.w = cvtpk(s[2 * j + 1][2], s[2 * j + 1][3]); pf[j] = __builtin_bit_cast(ab8, w); }
; }
; template <bool PV, bool WITHL>
; DEV void pv64(const LAS unsigned char* Vb, const AttnCtx& C, const ab8 (&pf)[2][2], f32x4 (&O)[2][4], f32x4 (&L)[2], bool a0, bool a1) {
;     if (PV) {
;         const int vr = 4 * C.q4 + (C.n >> 2), vc = (C.n & 3) >> 1, vs = 8 * (C.n & 1);
;         ab8 vf[4][2];
; #pragma unroll
;         for (int dt = 0; dt < 4; ++dt)
; #pragma unroll
;             for (int j = 0; j < 2; ++j) {
;                 const s16x4 lo = vtr(Vb + swz(32 * j + vr, 2 * dt + vc) + vs), hi = vtr(Vb + swz(32 * j + 16 + vr, 2 * dt + vc) + vs);
;                 vf[dt][j] = __builtin_shufflevector(lo, hi, 0, 1, 2, 3, 4, 5, 6, 7); }
;         __builtin_amdgcn_sched_barrier(0);
; #pragma unroll
;         for (int dt = 0; dt < 4; ++dt)
; #pragma unroll
;             for (int j = 0; j < 2; ++j) {
;                 if (a0) O[0][dt] = __builtin_amdgcn_mfma_f32_16x16x32_bf16(vf[dt][j], pf[0][j], O[0][dt], 0, 0, 0);
;                 if (a1) O[1][dt] = __builtin_amdgcn_mfma_f32_16x16x32_bf16(vf[dt][j], pf[1][j], O[1][dt], 0, 0, 0); }
;     }
;     if (WITHL) {
;         const short one = (C.n == 0) ? (short)0x3F80 : (short)0; const ab8 ones = {one, one, one, one, one, one, one, one};
; #pragma unroll
;         for (int j = 0; j < 2; ++j) {
;             if (a0) L[0] = __builtin_amdgcn_mfma_f32_16x16x32_bf16(ones, pf[0][j], L[0], 0, 0, 0);
;             if (a1) L[1] = __builtin_amdgcn_mfma_f32_16x16x32_bf16(ones, pf[1][j], L[1], 0, 0, 0);
;         }
;     }
; }
.LBB0_1210:
	v_exp_f32_e32 v92, v92
	v_exp_f32_e32 v93, v93
	v_exp_f32_e32 v90, v90
	v_exp_f32_e32 v91, v91
	v_exp_f32_e32 v74, v74
	v_exp_f32_e32 v75, v75
	v_exp_f32_e32 v76, v76
	v_exp_f32_e32 v77, v77
	v_exp_f32_e32 v70, v70
	v_exp_f32_e32 v71, v71
	v_exp_f32_e32 v72, v72
	v_exp_f32_e32 v73, v73
	v_exp_f32_e32 v102, v66
	v_exp_f32_e32 v103, v67
	v_exp_f32_e32 v104, v68
	v_exp_f32_e32 v105, v69
	v_add_u32_e32 v110, s27, v200
	v_cvt_pk_bf16_f32 v67, v92, v93
	v_add3_u32 v92, v110, v201, v209
	v_add3_u32 v108, v110, v202, v209
	v_add3_u32 v111, v110, v203, v209
	v_add3_u32 v110, v110, v204, v209
	v_cvt_pk_bf16_f32 v66, v90, v91
	v_cvt_pk_bf16_f32 v68, v74, v75
	v_cvt_pk_bf16_f32 v69, v76, v77
	v_cvt_pk_bf16_f32 v70, v70, v71
	v_cvt_pk_bf16_f32 v71, v72, v73
	v_cvt_pk_bf16_f32 v72, v102, v103
	v_cvt_pk_bf16_f32 v73, v104, v105
	ds_read_b64_tr_b16 v[74:75], v92 offset:24576
	ds_read_b64_tr_b16 v[76:77], v92 offset:26624
	ds_read_b64_tr_b16 v[90:91], v92 offset:28672
	ds_read_b64_tr_b16 v[92:93], v92 offset:30720
	ds_read_b64_tr_b16 v[102:103], v108 offset:24576
	ds_read_b64_tr_b16 v[104:105], v108 offset:26624
	ds_read_b64_tr_b16 v[106:107], v108 offset:28672
	ds_read_b64_tr_b16 v[108:109], v108 offset:30720
	ds_read_b64_tr_b16 v[114:115], v111 offset:24576
	ds_read_b64_tr_b16 v[116:117], v111 offset:26624
	ds_read_b64_tr_b16 v[118:119], v111 offset:28672
	ds_read_b64_tr_b16 v[120:121], v111 offset:30720
	ds_read_b64_tr_b16 v[130:131], v110 offset:24576
	ds_read_b64_tr_b16 v[132:133], v110 offset:26624
	ds_read_b64_tr_b16 v[134:135], v110 offset:28672
	ds_read_b64_tr_b16 v[136:137], v110 offset:30720
	s_waitcnt lgkmcnt(14)
	v_mfma_f32_16x16x32_bf16 v[74:77], v[74:77], v[66:69], v[78:81]
	v_mov_b32_e32 v216, v212
	s_waitcnt lgkmcnt(12)
	v_mfma_f32_16x16x32_bf16 v[110:113], v[90:93], v[70:73], v[74:77]
	s_waitcnt lgkmcnt(10)
	v_mfma_f32_16x16x32_bf16 v[74:77], v[102:105], v[66:69], v[82:85]
	v_mov_b64_e32 v[104:105], v[36:37]
	v_mov_b64_e32 v[102:103], v[34:35]
	s_waitcnt lgkmcnt(8)
	v_mfma_f32_16x16x32_bf16 v[122:125], v[106:109], v[70:73], v[74:77]
	v_mov_b64_e32 v[108:109], v[32:33]
	v_mov_b64_e32 v[106:107], v[30:31]
	s_waitcnt lgkmcnt(6)
	v_mfma_f32_16x16x32_bf16 v[74:77], v[114:117], v[66:69], v[86:89]
	v_mov_b64_e32 v[116:117], v[44:45]
	v_mov_b64_e32 v[114:115], v[42:43]
	s_waitcnt lgkmcnt(4)
	v_mfma_f32_16x16x32_bf16 v[126:129], v[118:121], v[70:73], v[74:77]
	v_mov_b64_e32 v[120:121], v[28:29]
	v_mov_b64_e32 v[118:119], v[26:27]
	s_waitcnt lgkmcnt(2)
	v_mfma_f32_16x16x32_bf16 v[74:77], v[130:133], v[66:69], v[94:97]
	v_mfma_f32_16x16x32_bf16 v[66:69], v[22:25], v[66:69], v[98:101]
	s_waitcnt lgkmcnt(0)
	v_mfma_f32_16x16x32_bf16 v[130:133], v[134:137], v[70:73], v[74:77]
	s_nop 0
	v_mov_b64_e32 v[100:101], v[40:41]
	v_mov_b64_e32 v[98:99], v[38:39]
	v_mfma_f32_16x16x32_bf16 v[134:137], v[22:25], v[70:73], v[66:69]

; #define LAS __attribute__((address_space(3)))
; DEV s16x4 vtr(const LAS unsigned char* p) { typedef short v4i16_t __attribute__((ext_vector_type(4))); return __builtin_bit_cast(s16x4, __builtin_amdgcn_ds_read_tr16_b64_v4i16((LAS v4i16_t*)p)); }
; DEV void ref_step(f32x4 (&s)[4], float& m, f32x4 (&O)[4], f32x4& L, ab8 (&pf)[2], bool colact) {
;     ...
; #pragma unroll
;     for (int kt = 0; kt < 4; ++kt)
; #pragma unroll
;         for (int i = 0; i < 4; ++i) s[kt][i] = __builtin_amdgcn_exp2f(s[kt][i]);
; #pragma unroll
;     for (int j = 0; j < 2; ++j) { v4u w; w.x = cvtpk(s[2 * j][0], s[2 * j][1]); w.y = cvtpk(s[2 * j][2], s[2 * j][3]); w.z = cvtpk(s[2 * j + 1][0], s[2 * j + 1][1]); w.w = cvtpk(s[2 * j + 1][2], s[2 * j + 1][3]); pf[j] = __builtin_bit_cast(ab8, w); }
; }
; template <bool PV, bool WITHL>
; DEV void pv64(const LAS unsigned char* Vb, const AttnCtx& C, const ab8 (&pf)[2][2], f32x4 (&O)[2][4], f32x4 (&L)[2], bool a0, bool a1) {
;     if (PV) {
;         const int vr = 4 * C.q4 + (C.n >> 2), vc = (C.n & 3) >> 1, vs = 8 * (C.n & 1);
;         ab8 vf[4][2];
; #pragma unroll
;         for (int dt = 0; dt < 4; ++dt)
; #pragma unroll
;             for (int j = 0; j < 2; ++j) {
;                 const s16x4 lo = vtr(Vb + swz(32 * j + vr, 2 * dt + vc) + vs), hi = vtr(Vb + swz(32 * j + 16 + vr, 2 * dt + vc) + vs);
;                 vf[dt][j] = __builtin_shufflevector(lo, hi, 0, 1, 2, 3, 4, 5, 6, 7); }
;         __builtin_amdgcn_sched_barrier(0);
; #pragma unroll
;         for (int dt = 0; dt < 4; ++dt)
; #pragma unroll
;             for (int j = 0; j < 2; ++j) {
;                 if (a0) O[0][dt] = __builtin_amdgcn_mfma_f32_16x16x32_bf16(vf[dt][j], pf[0][j], O[0][dt], 0, 0, 0);
;                 if (a1) O[1][dt] = __builtin_amdgcn_mfma_f32_16x16x32_bf16(vf[dt][j], pf[1][j], O[1][dt], 0, 0, 0); }
;     }
;     if (WITHL) {
;         const short one = (C.n == 0) ? (short)0x3F80 : (short)0; const ab8 ones = {one, one, one, one, one, one, one, one};
; #pragma unroll
;         for (int j = 0; j < 2; ++j) {
;             if (a0) L[0] = __builtin_amdgcn_mfma_f32_16x16x32_bf16(ones, pf[0][j], L[0], 0, 0, 0);
;             if (a1) L[1] = __builtin_amdgcn_mfma_f32_16x16x32_bf16(ones, pf[1][j], L[1], 0, 0, 0);
;         }
;     }
; }
.LBB0_1220:
	v_exp_f32_e32 v82, v82
	v_exp_f32_e32 v83, v83
	v_exp_f32_e32 v84, v84
	v_exp_f32_e32 v85, v85
	v_exp_f32_e32 v88, v88
	v_exp_f32_e32 v89, v89
	v_exp_f32_e32 v96, v96
	v_exp_f32_e32 v97, v97
	v_exp_f32_e32 v66, v66
	v_exp_f32_e32 v67, v67
	v_exp_f32_e32 v68, v68
	v_exp_f32_e32 v69, v69
	v_exp_f32_e32 v72, v72
	v_exp_f32_e32 v73, v73
	v_exp_f32_e32 v80, v80
	v_exp_f32_e32 v81, v81
	v_exp_f32_e32 v86, v86
	v_exp_f32_e32 v87, v87
	v_exp_f32_e32 v90, v90
	v_exp_f32_e32 v91, v91
	v_exp_f32_e32 v92, v92
	v_exp_f32_e32 v93, v93
	v_exp_f32_e32 v94, v94
	v_exp_f32_e32 v95, v95
	v_exp_f32_e32 v70, v70
	v_exp_f32_e32 v71, v71
	v_exp_f32_e32 v74, v74
	v_exp_f32_e32 v75, v75
	v_exp_f32_e32 v76, v76
	v_exp_f32_e32 v77, v77
	v_exp_f32_e32 v78, v78
	v_exp_f32_e32 v79, v79
	v_add_u32_e32 v98, s27, v200
	v_cvt_pk_bf16_f32 v82, v82, v83
	v_cvt_pk_bf16_f32 v83, v84, v85
	v_cvt_pk_bf16_f32 v85, v88, v89
	v_cvt_pk_bf16_f32 v89, v96, v97
	v_cvt_pk_bf16_f32 v66, v66, v67
	v_cvt_pk_bf16_f32 v67, v68, v69
	v_cvt_pk_bf16_f32 v69, v72, v73
	v_cvt_pk_bf16_f32 v73, v80, v81
	v_add3_u32 v80, v98, v201, v209
	v_add3_u32 v96, v98, v202, v209
	v_add3_u32 v99, v98, v203, v209
	v_add3_u32 v98, v98, v204, v209
	v_cvt_pk_bf16_f32 v84, v86, v87
	v_cvt_pk_bf16_f32 v86, v90, v91
	v_cvt_pk_bf16_f32 v87, v92, v93
	v_cvt_pk_bf16_f32 v88, v94, v95
	v_cvt_pk_bf16_f32 v68, v70, v71
	v_cvt_pk_bf16_f32 v70, v74, v75
	v_cvt_pk_bf16_f32 v71, v76, v77
	v_cvt_pk_bf16_f32 v72, v78, v79
	ds_read_b64_tr_b16 v[74:75], v80 offset:24576
	ds_read_b64_tr_b16 v[76:77], v80 offset:26624
	ds_read_b64_tr_b16 v[78:79], v80 offset:28672
	ds_read_b64_tr_b16 v[80:81], v80 offset:30720
	ds_read_b64_tr_b16 v[90:91], v96 offset:24576
	ds_read_b64_tr_b16 v[92:93], v96 offset:26624
	ds_read_b64_tr_b16 v[94:95], v96 offset:28672
	ds_read_b64_tr_b16 v[96:97], v96 offset:30720
	ds_read_b64_tr_b16 v[106:107], v99 offset:24576
	ds_read_b64_tr_b16 v[108:109], v99 offset:26624
	ds_read_b64_tr_b16 v[114:115], v99 offset:28672
	ds_read_b64_tr_b16 v[116:117], v99 offset:30720
	ds_read_b64_tr_b16 v[118:119], v98 offset:24576
	ds_read_b64_tr_b16 v[120:121], v98 offset:26624
	ds_read_b64_tr_b16 v[134:135], v98 offset:28672
	ds_read_b64_tr_b16 v[136:137], v98 offset:30720
	s_waitcnt lgkmcnt(10)
	v_mfma_f32_16x16x32_bf16 v[34:37], v[90:93], v[66:69], v[34:37]
	v_mov_b32_e32 v216, v212
	s_waitcnt lgkmcnt(6)
	v_mfma_f32_16x16x32_bf16 v[30:33], v[106:109], v[66:69], v[30:33]
	v_mfma_f32_16x16x32_bf16 v[38:41], v[74:77], v[66:69], v[38:41]
	v_mfma_f32_16x16x32_bf16 v[102:105], v[94:97], v[70:73], v[34:37]
	v_mfma_f32_16x16x32_bf16 v[34:37], v[106:109], v[82:85], v[50:53]
	s_waitcnt lgkmcnt(4)
	v_mfma_f32_16x16x32_bf16 v[106:109], v[114:117], v[70:73], v[30:33]
	s_waitcnt lgkmcnt(2)
	v_mfma_f32_16x16x32_bf16 v[30:33], v[118:121], v[82:85], v[46:49]
	v_mfma_f32_16x16x32_bf16 v[26:29], v[118:121], v[66:69], v[26:29]
	v_mfma_f32_16x16x32_bf16 v[62:65], v[74:77], v[82:85], v[62:65]
	v_mfma_f32_16x16x32_bf16 v[98:101], v[78:81], v[70:73], v[38:41]
	v_mfma_f32_16x16x32_bf16 v[38:41], v[90:93], v[82:85], v[54:57]
	s_waitcnt lgkmcnt(0)
	v_mfma_f32_16x16x32_bf16 v[130:133], v[134:137], v[86:89], v[30:33]
	v_mfma_f32_16x16x32_bf16 v[118:121], v[134:137], v[70:73], v[26:29]
	v_mfma_f32_16x16x32_bf16 v[26:29], v[22:25], v[82:85], v[58:61]
	v_mfma_f32_16x16x32_bf16 v[30:33], v[22:25], v[66:69], v[42:45]
	v_mfma_f32_16x16x32_bf16 v[110:113], v[78:81], v[86:89], v[62:65]
	v_mfma_f32_16x16x32_bf16 v[122:125], v[94:97], v[86:89], v[38:41]
	v_mfma_f32_16x16x32_bf16 v[126:129], v[114:117], v[86:89], v[34:37]
	v_mfma_f32_16x16x32_bf16 v[134:137], v[22:25], v[86:89], v[26:29]
	v_mfma_f32_16x16x32_bf16 v[114:117], v[22:25], v[70:73], v[30:33]

; DEV void ref_step(f32x4 (&s)[4], float& m, f32x4 (&O)[4], f32x4& L, ab8 (&pf)[2], bool colact) {
;     float mx = fmaxf(fmaxf(s[0][0], s[0][1]), fmaxf(s[0][2], s[0][3]));
; #pragma unroll
;     for (int kt = 1; kt < 4; ++kt) mx = fmaxf(mx, fmaxf(fmaxf(s[kt][0], s[kt][1]), fmaxf(s[kt][2], s[kt][3])));
;     const bool slow = (colact && m == NEG_INF) || mx > 64.f;
;     if (__any(slow)) {
;         mx = fmaxf(mx, __shfl_xor(mx, 16)); mx = fmaxf(mx, __shfl_xor(mx, 32));
;         const bool un = (m == NEG_INF);
;         const float d = (mx == NEG_INF) ? 0.f : (un ? mx : fmaxf(mx, 0.f));
;         const float sc = un ? 1.f : __builtin_amdgcn_exp2f(-d);
; #pragma unroll
;         for (int kt = 0; kt < 4; ++kt) s[kt] = s[kt] - d;
; #pragma unroll
;         for (int dt = 0; dt < 4; ++dt) O[dt] = O[dt] * sc;
;         L = L * sc;
;         m = un ? ((mx == NEG_INF) ? NEG_INF : mx) : m + d;
;     }
; #pragma unroll
;     for (int kt = 0; kt < 4; ++kt)
; #pragma unroll
;         for (int i = 0; i < 4; ++i) s[kt][i] = __builtin_amdgcn_exp2f(s[kt][i]);
; #pragma unroll
;     for (int j = 0; j < 2; ++j) { v4u w; w.x = cvtpk(s[2 * j][0], s[2 * j][1]); w.y = cvtpk(s[2 * j][2], s[2 * j][3]); w.z = cvtpk(s[2 * j + 1][0], s[2 * j + 1][1]); w.w = cvtpk(s[2 * j + 1][2], s[2 * j + 1][3]); pf[j] = __builtin_bit_cast(ab8, w); }
; }
; template <bool PV, bool WITHL>
; DEV void pv64(const LAS unsigned char* Vb, const AttnCtx& C, const ab8 (&pf)[2][2], f32x4 (&O)[2][4], f32x4 (&L)[2], bool a0, bool a1) {
;     if (PV) {
;         const int vr = 4 * C.q4 + (C.n >> 2), vc = (C.n & 3) >> 1, vs = 8 * (C.n & 1);
;         ab8 vf[4][2];
; #pragma unroll
;         for (int dt = 0; dt < 4; ++dt)
; #pragma unroll
;             for (int j = 0; j < 2; ++j) {
;                 const s16x4 lo = vtr(Vb + swz(32 * j + vr, 2 * dt + vc) + vs), hi = vtr(Vb + swz(32 * j + 16 + vr, 2 * dt + vc) + vs);
;                 vf[dt][j] = __builtin_shufflevector(lo, hi, 0, 1, 2, 3, 4, 5, 6, 7); }
; DEV void attn_unit_mfma(Frame& F, int qg, int kv) {
;     ...
;         if (a0 || a1) {
;             const bool near = j >= cur - 2; const float bi = near ? 0.f : C.b31;
;             const bool c0 = ((byte >> (C.n >> 2)) & 1u) != 0u, c1 = ((byte >> (4 + (C.n >> 2))) & 1u) != 0u;
;     ...
;             if (a0 && a1) SEL_BODY(true, true); else if (a0) SEL_BODY(true, false); else SEL_BODY(false, true);
.Lmy_fb_2:
	v_add3_u32 v236, s27, v199, v198
	v_add3_u32 v237, s27, v197, v198
	ds_read_b128 v[66:69], v236 offset:32768
	ds_read_b128 v[70:73], v237 offset:32768
	ds_read_b128 v[74:77], v236 offset:34816
	ds_read_b128 v[78:81], v237 offset:34816
	ds_read_b128 v[82:85], v236 offset:36864
	ds_read_b128 v[86:89], v237 offset:36864
	ds_read_b128 v[90:93], v236 offset:38912
	ds_read_b128 v[94:97], v237 offset:38912
	v_and_b32_e32 v243, s8, v206
	v_and_b32_e32 v244, s8, v207
	v_cmp_ne_u32_e64 s[10:11], 0, v243
	v_cmp_ne_u32_e64 s[14:15], 0, v244
	v_cmp_eq_f32_e64 s[12:13], s3, v213
	v_cmp_eq_f32_e64 s[16:17], s3, v212
	v_add_u32_e32 v238, s27, v200
	v_add3_u32 v239, v238, v201, v209
	v_add3_u32 v240, v238, v202, v209
	v_cndmask_b32_e64 v228, v213, 0, s[12:13]
	v_cndmask_b32_e64 v232, v212, 0, s[16:17]
	v_sub_f32_e32 v228, v175, v228
	v_sub_f32_e32 v232, v175, v232
	v_add3_u32 v241, v238, v203, v209
	v_add3_u32 v242, v238, v204, v209
	v_cndmask_b32_e64 v228, v173, v228, s[10:11]
	v_cndmask_b32_e64 v232, v173, v232, s[14:15]
	s_and_b64 s[12:13], s[10:11], s[12:13]
	s_and_b64 s[16:17], s[14:15], s[16:17]
	s_or_b64 s[12:13], s[12:13], s[16:17]
	v_mov_b32_e32 v229, v228
	v_mov_b32_e32 v230, v228
	v_mov_b32_e32 v231, v228
	v_mov_b32_e32 v233, v232
	v_mov_b32_e32 v234, v232
	v_mov_b32_e32 v235, v232
	s_waitcnt lgkmcnt(0)
	v_mfma_f32_16x16x32_bf16 v[98:101], v[66:69], v[10:13], v[232:235]
	v_mfma_f32_16x16x32_bf16 v[102:105], v[74:77], v[10:13], v[232:235]
	v_mfma_f32_16x16x32_bf16 v[106:109], v[82:85], v[10:13], v[232:235]
	v_mfma_f32_16x16x32_bf16 v[110:113], v[90:93], v[10:13], v[232:235]
	v_mfma_f32_16x16x32_bf16 v[66:69], v[66:69], v[2:5], v[228:231]
	v_mfma_f32_16x16x32_bf16 v[74:77], v[74:77], v[2:5], v[228:231]
	v_mfma_f32_16x16x32_bf16 v[82:85], v[82:85], v[2:5], v[228:231]
	v_mfma_f32_16x16x32_bf16 v[90:93], v[90:93], v[2:5], v[228:231]
	v_mfma_f32_16x16x32_bf16 v[66:69], v[70:73], v[6:9], v[66:69]
	v_mfma_f32_16x16x32_bf16 v[74:77], v[78:81], v[6:9], v[74:77]
	v_mfma_f32_16x16x32_bf16 v[82:85], v[86:89], v[6:9], v[82:85]
	v_mfma_f32_16x16x32_bf16 v[90:93], v[94:97], v[6:9], v[90:93]
	v_mfma_f32_16x16x32_bf16 v[70:73], v[70:73], v[14:17], v[98:101]
	v_mfma_f32_16x16x32_bf16 v[78:81], v[78:81], v[14:17], v[102:105]
	v_mfma_f32_16x16x32_bf16 v[86:89], v[86:89], v[14:17], v[106:109]
	v_mfma_f32_16x16x32_bf16 v[94:97], v[94:97], v[14:17], v[110:113]
	ds_read_b64_tr_b16 v[114:115], v241 offset:40960
	ds_read_b64_tr_b16 v[116:117], v241 offset:43008
	ds_read_b64_tr_b16 v[118:119], v241 offset:45056
	ds_read_b64_tr_b16 v[120:121], v241 offset:47104
	ds_read_b64_tr_b16 v[122:123], v242 offset:40960
	ds_read_b64_tr_b16 v[124:125], v242 offset:43008
	ds_read_b64_tr_b16 v[126:127], v242 offset:45056
	ds_read_b64_tr_b16 v[128:129], v242 offset:47104
	ds_read_b64_tr_b16 v[98:99], v239 offset:40960
	ds_read_b64_tr_b16 v[100:101], v239 offset:43008
	ds_read_b64_tr_b16 v[102:103], v239 offset:45056
	ds_read_b64_tr_b16 v[104:105], v239 offset:47104
	ds_read_b64_tr_b16 v[106:107], v240 offset:40960
	ds_read_b64_tr_b16 v[108:109], v240 offset:43008
	ds_read_b64_tr_b16 v[110:111], v240 offset:45056
	ds_read_b64_tr_b16 v[112:113], v240 offset:47104
	v_max3_f32 v243, v66, v67, v68
	v_max3_f32 v244, v69, v74, v75
	v_max3_f32 v245, v76, v77, v82
	v_max3_f32 v246, v83, v84, v85
	v_max3_f32 v243, v243, v244, v90
	v_max3_f32 v245, v245, v246, v91
	v_max3_f32 v243, v243, v92, v93
	v_max_f32_e32 v243, v243, v245
	v_cmp_lt_f32_e32 vcc, s96, v243
	s_or_b64 s[12:13], s[12:13], vcc
	v_max3_f32 v243, v70, v71, v72
	v_max3_f32 v244, v73, v78, v79
	v_max3_f32 v245, v80, v81, v86
	v_max3_f32 v246, v87, v88, v89
	v_max3_f32 v243, v243, v244, v94
	v_max3_f32 v245, v245, v246, v95
	v_max3_f32 v243, v243, v96, v97
	v_max_f32_e32 v243, v243, v245
	v_cmp_lt_f32_e32 vcc, s96, v243
	s_or_b64 s[12:13], s[12:13], vcc
	s_cmp_lg_u64 s[12:13], 0
	s_cbranch_scc1 .Lmy_slow_b_2
	v_exp_f32_e32 v66, v66
	v_exp_f32_e32 v67, v67
	v_exp_f32_e32 v68, v68
	v_exp_f32_e32 v69, v69
	v_exp_f32_e32 v74, v74
	v_exp_f32_e32 v75, v75
	v_exp_f32_e32 v76, v76
	v_exp_f32_e32 v77, v77
	v_exp_f32_e32 v82, v82
	v_exp_f32_e32 v83, v83
	v_exp_f32_e32 v84, v84
	v_exp_f32_e32 v85, v85
	v_exp_f32_e32 v90, v90
	v_exp_f32_e32 v91, v91
	v_exp_f32_e32 v92, v92
	v_exp_f32_e32 v93, v93
	v_exp_f32_e32 v70, v70
	v_exp_f32_e32 v71, v71
	v_exp_f32_e32 v72, v72
	v_exp_f32_e32 v73, v73
	v_exp_f32_e32 v78, v78
	v_exp_f32_e32 v79, v79
	v_exp_f32_e32 v80, v80
	v_exp_f32_e32 v81, v81
	v_exp_f32_e32 v86, v86
	v_exp_f32_e32 v87, v87
	v_exp_f32_e32 v88, v88
	v_exp_f32_e32 v89, v89
	v_exp_f32_e32 v94, v94
	v_exp_f32_e32 v95, v95
	v_exp_f32_e32 v96, v96
	v_exp_f32_e32 v97, v97
	v_cvt_pk_bf16_f32 v130, v66, v67
	v_cvt_pk_bf16_f32 v131, v68, v69
	v_cvt_pk_bf16_f32 v132, v74, v75
	v_cvt_pk_bf16_f32 v133, v76, v77
	v_cvt_pk_bf16_f32 v134, v82, v83
	v_cvt_pk_bf16_f32 v135, v84, v85
	v_cvt_pk_bf16_f32 v136, v90, v91
	v_cvt_pk_bf16_f32 v137, v92, v93
	v_cvt_pk_bf16_f32 v228, v70, v71
	v_cvt_pk_bf16_f32 v229, v72, v73
	v_cvt_pk_bf16_f32 v230, v78, v79
	v_cvt_pk_bf16_f32 v231, v80, v81
	v_cvt_pk_bf16_f32 v232, v86, v87
	v_cvt_pk_bf16_f32 v233, v88, v89
	v_cvt_pk_bf16_f32 v234, v94, v95
	v_cvt_pk_bf16_f32 v235, v96, v97
	s_nop 1
	s_waitcnt lgkmcnt(12)
	v_mfma_f32_16x16x32_bf16 v[50:53], v[114:117], v[130:133], v[50:53]
	v_mfma_f32_16x16x32_bf16 v[30:33], v[114:117], v[228:231], v[30:33]
	v_mfma_f32_16x16x32_bf16 v[58:61], v[22:25], v[130:133], v[58:61]
	v_mfma_f32_16x16x32_bf16 v[42:45], v[22:25], v[228:231], v[42:45]
	v_mfma_f32_16x16x32_bf16 v[50:53], v[118:121], v[134:137], v[50:53]
	v_mfma_f32_16x16x32_bf16 v[30:33], v[118:121], v[232:235], v[30:33]
	s_waitcnt lgkmcnt(8)
	v_mfma_f32_16x16x32_bf16 v[46:49], v[122:125], v[130:133], v[46:49]
	v_mfma_f32_16x16x32_bf16 v[26:29], v[122:125], v[228:231], v[26:29]
	v_mfma_f32_16x16x32_bf16 v[46:49], v[126:129], v[134:137], v[46:49]
	v_mfma_f32_16x16x32_bf16 v[26:29], v[126:129], v[232:235], v[26:29]
	s_waitcnt lgkmcnt(4)
	v_mfma_f32_16x16x32_bf16 v[62:65], v[98:101], v[130:133], v[62:65]
	v_mfma_f32_16x16x32_bf16 v[38:41], v[98:101], v[228:231], v[38:41]
	v_mfma_f32_16x16x32_bf16 v[58:61], v[22:25], v[134:137], v[58:61]
	v_mfma_f32_16x16x32_bf16 v[42:45], v[22:25], v[232:235], v[42:45]
	v_mfma_f32_16x16x32_bf16 v[62:65], v[102:105], v[134:137], v[62:65]
	v_mfma_f32_16x16x32_bf16 v[38:41], v[102:105], v[232:235], v[38:41]
	s_waitcnt lgkmcnt(0)
	v_mfma_f32_16x16x32_bf16 v[54:57], v[106:109], v[130:133], v[54:57]
	v_mfma_f32_16x16x32_bf16 v[34:37], v[106:109], v[228:231], v[34:37]
	v_mfma_f32_16x16x32_bf16 v[54:57], v[110:113], v[134:137], v[54:57]
	v_mfma_f32_16x16x32_bf16 v[34:37], v[110:113], v[232:235], v[34:37]
	s_nop 7
	s_branch .LBB0_1248

; #define LAS __attribute__((address_space(3)))
; DEV s16x4 vtr(const LAS unsigned char* p) { typedef short v4i16_t __attribute__((ext_vector_type(4))); return __builtin_bit_cast(s16x4, __builtin_amdgcn_ds_read_tr16_b64_v4i16((LAS v4i16_t*)p)); }
; DEV void ref_step(f32x4 (&s)[4], float& m, f32x4 (&O)[4], f32x4& L, ab8 (&pf)[2], bool colact) {
;     ...
;     for (int kt = 0; kt < 4; ++kt)
; #pragma unroll
;         for (int i = 0; i < 4; ++i) s[kt][i] = __builtin_amdgcn_exp2f(s[kt][i]);
; #pragma unroll
;     for (int j = 0; j < 2; ++j) { v4u w; w.x = cvtpk(s[2 * j][0], s[2 * j][1]); w.y = cvtpk(s[2 * j][2], s[2 * j][3]); w.z = cvtpk(s[2 * j + 1][0], s[2 * j + 1][1]); w.w = cvtpk(s[2 * j + 1][2], s[2 * j + 1][3]); pf[j] = __builtin_bit_cast(ab8, w); }
; }
; template <bool PV, bool WITHL>
; DEV void pv64(const LAS unsigned char* Vb, const AttnCtx& C, const ab8 (&pf)[2][2], f32x4 (&O)[2][4], f32x4 (&L)[2], bool a0, bool a1) {
;     if (PV) {
;         const int vr = 4 * C.q4 + (C.n >> 2), vc = (C.n & 3) >> 1, vs = 8 * (C.n & 1);
;         ab8 vf[4][2];
; #pragma unroll
;         for (int dt = 0; dt < 4; ++dt)
; #pragma unroll
;             for (int j = 0; j < 2; ++j) {
;                 const s16x4 lo = vtr(Vb + swz(32 * j + vr, 2 * dt + vc) + vs), hi = vtr(Vb + swz(32 * j + 16 + vr, 2 * dt + vc) + vs);
;                 vf[dt][j] = __builtin_shufflevector(lo, hi, 0, 1, 2, 3, 4, 5, 6, 7); }
;         __builtin_amdgcn_sched_barrier(0);
; #pragma unroll
;         for (int dt = 0; dt < 4; ++dt)
; #pragma unroll
;             for (int j = 0; j < 2; ++j) {
;                 if (a0) O[0][dt] = __builtin_amdgcn_mfma_f32_16x16x32_bf16(vf[dt][j], pf[0][j], O[0][dt], 0, 0, 0);
;                 if (a1) O[1][dt] = __builtin_amdgcn_mfma_f32_16x16x32_bf16(vf[dt][j], pf[1][j], O[1][dt], 0, 0, 0); }
;     }
;     if (WITHL) {
;         const short one = (C.n == 0) ? (short)0x3F80 : (short)0; const ab8 ones = {one, one, one, one, one, one, one, one};
; #pragma unroll
;         for (int j = 0; j < 2; ++j) {
;             if (a0) L[0] = __builtin_amdgcn_mfma_f32_16x16x32_bf16(ones, pf[0][j], L[0], 0, 0, 0);
;             if (a1) L[1] = __builtin_amdgcn_mfma_f32_16x16x32_bf16(ones, pf[1][j], L[1], 0, 0, 0);
;         }
;     }
.LBB0_1230:
	v_exp_f32_e32 v104, v104
	v_exp_f32_e32 v105, v105
	v_exp_f32_e32 v110, v110
	v_exp_f32_e32 v111, v111
	v_exp_f32_e32 v112, v112
	v_exp_f32_e32 v113, v113
	v_exp_f32_e32 v106, v106
	v_exp_f32_e32 v107, v107
	v_exp_f32_e32 v108, v108
	v_exp_f32_e32 v109, v109
	v_exp_f32_e32 v98, v98
	v_exp_f32_e32 v99, v99
	v_exp_f32_e32 v100, v100
	v_exp_f32_e32 v101, v101
	v_exp_f32_e32 v102, v102
	v_exp_f32_e32 v103, v103
	v_add_u32_e32 v217, s27, v200
	v_cvt_pk_bf16_f32 v137, v104, v105
	v_add3_u32 v104, v217, v201, v209
	v_add3_u32 v227, v217, v202, v209
	v_cvt_pk_bf16_f32 v110, v110, v111
	v_cvt_pk_bf16_f32 v111, v112, v113
	v_cvt_pk_bf16_f32 v112, v106, v107
	v_cvt_pk_bf16_f32 v113, v108, v109
	v_cvt_pk_bf16_f32 v134, v98, v99
	v_cvt_pk_bf16_f32 v135, v100, v101
	v_cvt_pk_bf16_f32 v136, v102, v103
	ds_read_b64_tr_b16 v[98:99], v104 offset:40960
	ds_read_b64_tr_b16 v[100:101], v104 offset:43008
	ds_read_b64_tr_b16 v[102:103], v104 offset:45056
	ds_read_b64_tr_b16 v[104:105], v104 offset:47104
	ds_read_b64_tr_b16 v[106:107], v227 offset:40960
	ds_read_b64_tr_b16 v[108:109], v227 offset:43008
	ds_read_b64_tr_b16 v[228:229], v227 offset:45056
	ds_read_b64_tr_b16 v[230:231], v227 offset:47104
	v_add3_u32 v227, v217, v203, v209
	v_add3_u32 v217, v217, v204, v209
	ds_read_b64_tr_b16 v[232:233], v227 offset:40960
	ds_read_b64_tr_b16 v[234:235], v227 offset:43008
	ds_read_b64_tr_b16 v[236:237], v227 offset:45056
	ds_read_b64_tr_b16 v[238:239], v227 offset:47104
	ds_read_b64_tr_b16 v[240:241], v217 offset:40960
	ds_read_b64_tr_b16 v[242:243], v217 offset:43008
	ds_read_b64_tr_b16 v[244:245], v217 offset:45056
	ds_read_b64_tr_b16 v[246:247], v217 offset:47104
	s_waitcnt lgkmcnt(14)
	v_mfma_f32_16x16x32_bf16 v[98:101], v[98:101], v[110:113], v[114:117]
	s_mov_b64 s[12:13], 0
	s_waitcnt lgkmcnt(12)
	v_mfma_f32_16x16x32_bf16 v[98:101], v[102:105], v[134:137], v[98:101]
	s_waitcnt lgkmcnt(10)
	v_mfma_f32_16x16x32_bf16 v[102:105], v[106:109], v[110:113], v[118:121]
	s_waitcnt lgkmcnt(6)
	v_mfma_f32_16x16x32_bf16 v[106:109], v[232:235], v[110:113], v[122:125]
	s_waitcnt lgkmcnt(2)
	v_mfma_f32_16x16x32_bf16 v[114:117], v[240:243], v[110:113], v[126:129]
	v_mfma_f32_16x16x32_bf16 v[110:113], v[22:25], v[110:113], v[130:133]
	v_mfma_f32_16x16x32_bf16 v[102:105], v[228:231], v[134:137], v[102:105]
	v_mfma_f32_16x16x32_bf16 v[106:109], v[236:239], v[134:137], v[106:109]
	s_waitcnt lgkmcnt(0)
	v_mfma_f32_16x16x32_bf16 v[118:121], v[244:247], v[134:137], v[114:117]
	v_mfma_f32_16x16x32_bf16 v[114:117], v[22:25], v[134:137], v[110:113]

; #define LAS __attribute__((address_space(3)))
; DEV s16x4 vtr(const LAS unsigned char* p) { typedef short v4i16_t __attribute__((ext_vector_type(4))); return __builtin_bit_cast(s16x4, __builtin_amdgcn_ds_read_tr16_b64_v4i16((LAS v4i16_t*)p)); }
; DEV void ref_step(f32x4 (&s)[4], float& m, f32x4 (&O)[4], f32x4& L, ab8 (&pf)[2], bool colact) {
;     ...
;     for (int kt = 0; kt < 4; ++kt)
; #pragma unroll
;         for (int i = 0; i < 4; ++i) s[kt][i] = __builtin_amdgcn_exp2f(s[kt][i]);
; #pragma unroll
;     for (int j = 0; j < 2; ++j) { v4u w; w.x = cvtpk(s[2 * j][0], s[2 * j][1]); w.y = cvtpk(s[2 * j][2], s[2 * j][3]); w.z = cvtpk(s[2 * j + 1][0], s[2 * j + 1][1]); w.w = cvtpk(s[2 * j + 1][2], s[2 * j + 1][3]); pf[j] = __builtin_bit_cast(ab8, w); }
; }
; template <bool PV, bool WITHL>
; DEV void pv64(const LAS unsigned char* Vb, const AttnCtx& C, const ab8 (&pf)[2][2], f32x4 (&O)[2][4], f32x4 (&L)[2], bool a0, bool a1) {
;     if (PV) {
;         const int vr = 4 * C.q4 + (C.n >> 2), vc = (C.n & 3) >> 1, vs = 8 * (C.n & 1);
;         ab8 vf[4][2];
; #pragma unroll
;         for (int dt = 0; dt < 4; ++dt)
; #pragma unroll
;             for (int j = 0; j < 2; ++j) {
;                 const s16x4 lo = vtr(Vb + swz(32 * j + vr, 2 * dt + vc) + vs), hi = vtr(Vb + swz(32 * j + 16 + vr, 2 * dt + vc) + vs);
;                 vf[dt][j] = __builtin_shufflevector(lo, hi, 0, 1, 2, 3, 4, 5, 6, 7); }
;         __builtin_amdgcn_sched_barrier(0);
; #pragma unroll
;         for (int dt = 0; dt < 4; ++dt)
; #pragma unroll
;             for (int j = 0; j < 2; ++j) {
;                 if (a0) O[0][dt] = __builtin_amdgcn_mfma_f32_16x16x32_bf16(vf[dt][j], pf[0][j], O[0][dt], 0, 0, 0);
;                 if (a1) O[1][dt] = __builtin_amdgcn_mfma_f32_16x16x32_bf16(vf[dt][j], pf[1][j], O[1][dt], 0, 0, 0); }
;     }
;     if (WITHL) {
;         const short one = (C.n == 0) ? (short)0x3F80 : (short)0; const ab8 ones = {one, one, one, one, one, one, one, one};
; #pragma unroll
;         for (int j = 0; j < 2; ++j) {
;             if (a0) L[0] = __builtin_amdgcn_mfma_f32_16x16x32_bf16(ones, pf[0][j], L[0], 0, 0, 0);
;             if (a1) L[1] = __builtin_amdgcn_mfma_f32_16x16x32_bf16(ones, pf[1][j], L[1], 0, 0, 0);
;         }
;     }
.LBB0_1236:
	v_exp_f32_e32 v92, v92
	v_exp_f32_e32 v93, v93
	v_exp_f32_e32 v90, v90
	v_exp_f32_e32 v91, v91
	v_exp_f32_e32 v74, v74
	v_exp_f32_e32 v75, v75
	v_exp_f32_e32 v76, v76
	v_exp_f32_e32 v77, v77
	v_exp_f32_e32 v70, v70
	v_exp_f32_e32 v71, v71
	v_exp_f32_e32 v72, v72
	v_exp_f32_e32 v73, v73
	v_exp_f32_e32 v102, v66
	v_exp_f32_e32 v103, v67
	v_exp_f32_e32 v104, v68
	v_exp_f32_e32 v105, v69
	v_add_u32_e32 v110, s27, v200
	v_cvt_pk_bf16_f32 v67, v92, v93
	v_add3_u32 v92, v110, v201, v209
	v_add3_u32 v108, v110, v202, v209
	v_add3_u32 v111, v110, v203, v209
	v_add3_u32 v110, v110, v204, v209
	v_cvt_pk_bf16_f32 v66, v90, v91
	v_cvt_pk_bf16_f32 v68, v74, v75
	v_cvt_pk_bf16_f32 v69, v76, v77
	v_cvt_pk_bf16_f32 v70, v70, v71
	v_cvt_pk_bf16_f32 v71, v72, v73
	v_cvt_pk_bf16_f32 v72, v102, v103
	v_cvt_pk_bf16_f32 v73, v104, v105
	ds_read_b64_tr_b16 v[74:75], v92 offset:40960
	ds_read_b64_tr_b16 v[76:77], v92 offset:43008
	ds_read_b64_tr_b16 v[90:91], v92 offset:45056
	ds_read_b64_tr_b16 v[92:93], v92 offset:47104
	ds_read_b64_tr_b16 v[102:103], v108 offset:40960
	ds_read_b64_tr_b16 v[104:105], v108 offset:43008
	ds_read_b64_tr_b16 v[106:107], v108 offset:45056
	ds_read_b64_tr_b16 v[108:109], v108 offset:47104
	ds_read_b64_tr_b16 v[114:115], v111 offset:40960
	ds_read_b64_tr_b16 v[116:117], v111 offset:43008
	ds_read_b64_tr_b16 v[118:119], v111 offset:45056
	ds_read_b64_tr_b16 v[120:121], v111 offset:47104
	ds_read_b64_tr_b16 v[130:131], v110 offset:40960
	ds_read_b64_tr_b16 v[132:133], v110 offset:43008
	ds_read_b64_tr_b16 v[134:135], v110 offset:45056
	ds_read_b64_tr_b16 v[136:137], v110 offset:47104
	s_waitcnt lgkmcnt(14)
	v_mfma_f32_16x16x32_bf16 v[74:77], v[74:77], v[66:69], v[78:81]
	v_mov_b32_e32 v218, v212
	s_waitcnt lgkmcnt(12)
	v_mfma_f32_16x16x32_bf16 v[110:113], v[90:93], v[70:73], v[74:77]
	s_waitcnt lgkmcnt(10)
	v_mfma_f32_16x16x32_bf16 v[74:77], v[102:105], v[66:69], v[82:85]
	v_mov_b64_e32 v[104:105], v[36:37]
	v_mov_b64_e32 v[102:103], v[34:35]
	s_waitcnt lgkmcnt(8)
	v_mfma_f32_16x16x32_bf16 v[122:125], v[106:109], v[70:73], v[74:77]
	v_mov_b64_e32 v[108:109], v[32:33]
	v_mov_b64_e32 v[106:107], v[30:31]
	s_waitcnt lgkmcnt(6)
	v_mfma_f32_16x16x32_bf16 v[74:77], v[114:117], v[66:69], v[86:89]
	v_mov_b64_e32 v[116:117], v[44:45]
	v_mov_b64_e32 v[114:115], v[42:43]
	s_waitcnt lgkmcnt(4)
	v_mfma_f32_16x16x32_bf16 v[126:129], v[118:121], v[70:73], v[74:77]
	v_mov_b64_e32 v[120:121], v[28:29]
	v_mov_b64_e32 v[118:119], v[26:27]
	s_waitcnt lgkmcnt(2)
	v_mfma_f32_16x16x32_bf16 v[74:77], v[130:133], v[66:69], v[94:97]
	v_mfma_f32_16x16x32_bf16 v[66:69], v[22:25], v[66:69], v[98:101]
	s_waitcnt lgkmcnt(0)
	v_mfma_f32_16x16x32_bf16 v[130:133], v[134:137], v[70:73], v[74:77]
	s_nop 0
	v_mov_b64_e32 v[100:101], v[40:41]
	v_mov_b64_e32 v[98:99], v[38:39]
	v_mfma_f32_16x16x32_bf16 v[134:137], v[22:25], v[70:73], v[66:69]

; #define LAS __attribute__((address_space(3)))
; DEV s16x4 vtr(const LAS unsigned char* p) { typedef short v4i16_t __attribute__((ext_vector_type(4))); return __builtin_bit_cast(s16x4, __builtin_amdgcn_ds_read_tr16_b64_v4i16((LAS v4i16_t*)p)); }
; DEV void ref_step(f32x4 (&s)[4], float& m, f32x4 (&O)[4], f32x4& L, ab8 (&pf)[2], bool colact) {
;     ...
;     for (int kt = 0; kt < 4; ++kt)
; #pragma unroll
;         for (int i = 0; i < 4; ++i) s[kt][i] = __builtin_amdgcn_exp2f(s[kt][i]);
; #pragma unroll
;     for (int j = 0; j < 2; ++j) { v4u w; w.x = cvtpk(s[2 * j][0], s[2 * j][1]); w.y = cvtpk(s[2 * j][2], s[2 * j][3]); w.z = cvtpk(s[2 * j + 1][0], s[2 * j + 1][1]); w.w = cvtpk(s[2 * j + 1][2], s[2 * j + 1][3]); pf[j] = __builtin_bit_cast(ab8, w); }
; }
; template <bool PV, bool WITHL>
; DEV void pv64(const LAS unsigned char* Vb, const AttnCtx& C, const ab8 (&pf)[2][2], f32x4 (&O)[2][4], f32x4 (&L)[2], bool a0, bool a1) {
;     if (PV) {
;         const int vr = 4 * C.q4 + (C.n >> 2), vc = (C.n & 3) >> 1, vs = 8 * (C.n & 1);
;         ab8 vf[4][2];
; #pragma unroll
;         for (int dt = 0; dt < 4; ++dt)
; #pragma unroll
;             for (int j = 0; j < 2; ++j) {
;                 const s16x4 lo = vtr(Vb + swz(32 * j + vr, 2 * dt + vc) + vs), hi = vtr(Vb + swz(32 * j + 16 + vr, 2 * dt + vc) + vs);
;                 vf[dt][j] = __builtin_shufflevector(lo, hi, 0, 1, 2, 3, 4, 5, 6, 7); }
;         __builtin_amdgcn_sched_barrier(0);
; #pragma unroll
;         for (int dt = 0; dt < 4; ++dt)
; #pragma unroll
;             for (int j = 0; j < 2; ++j) {
;                 if (a0) O[0][dt] = __builtin_amdgcn_mfma_f32_16x16x32_bf16(vf[dt][j], pf[0][j], O[0][dt], 0, 0, 0);
;                 if (a1) O[1][dt] = __builtin_amdgcn_mfma_f32_16x16x32_bf16(vf[dt][j], pf[1][j], O[1][dt], 0, 0, 0); }
;     }
;     if (WITHL) {
;         const short one = (C.n == 0) ? (short)0x3F80 : (short)0; const ab8 ones = {one, one, one, one, one, one, one, one};
; #pragma unroll
;         for (int j = 0; j < 2; ++j) {
;             if (a0) L[0] = __builtin_amdgcn_mfma_f32_16x16x32_bf16(ones, pf[0][j], L[0], 0, 0, 0);
;             if (a1) L[1] = __builtin_amdgcn_mfma_f32_16x16x32_bf16(ones, pf[1][j], L[1], 0, 0, 0);
;         }
;     }
.LBB0_1246:
	v_exp_f32_e32 v82, v82
	v_exp_f32_e32 v83, v83
	v_exp_f32_e32 v84, v84
	v_exp_f32_e32 v85, v85
	v_exp_f32_e32 v88, v88
	v_exp_f32_e32 v89, v89
	v_exp_f32_e32 v96, v96
	v_exp_f32_e32 v97, v97
	v_exp_f32_e32 v66, v66
	v_exp_f32_e32 v67, v67
	v_exp_f32_e32 v68, v68
	v_exp_f32_e32 v69, v69
	v_exp_f32_e32 v72, v72
	v_exp_f32_e32 v73, v73
	v_exp_f32_e32 v80, v80
	v_exp_f32_e32 v81, v81
	v_exp_f32_e32 v86, v86
	v_exp_f32_e32 v87, v87
	v_exp_f32_e32 v90, v90
	v_exp_f32_e32 v91, v91
	v_exp_f32_e32 v92, v92
	v_exp_f32_e32 v93, v93
	v_exp_f32_e32 v94, v94
	v_exp_f32_e32 v95, v95
	v_exp_f32_e32 v70, v70
	v_exp_f32_e32 v71, v71
	v_exp_f32_e32 v74, v74
	v_exp_f32_e32 v75, v75
	v_exp_f32_e32 v76, v76
	v_exp_f32_e32 v77, v77
	v_exp_f32_e32 v78, v78
	v_exp_f32_e32 v79, v79
	v_add_u32_e32 v98, s27, v200
	v_cvt_pk_bf16_f32 v82, v82, v83
	v_cvt_pk_bf16_f32 v83, v84, v85
	v_cvt_pk_bf16_f32 v85, v88, v89
	v_cvt_pk_bf16_f32 v89, v96, v97
	v_cvt_pk_bf16_f32 v66, v66, v67
	v_cvt_pk_bf16_f32 v67, v68, v69
	v_cvt_pk_bf16_f32 v69, v72, v73
	v_cvt_pk_bf16_f32 v73, v80, v81
	v_add3_u32 v80, v98, v201, v209
	v_add3_u32 v96, v98, v202, v209
	v_add3_u32 v99, v98, v203, v209
	v_add3_u32 v98, v98, v204, v209
	v_cvt_pk_bf16_f32 v84, v86, v87
	v_cvt_pk_bf16_f32 v86, v90, v91
	v_cvt_pk_bf16_f32 v87, v92, v93
	v_cvt_pk_bf16_f32 v88, v94, v95
	v_cvt_pk_bf16_f32 v68, v70, v71
	v_cvt_pk_bf16_f32 v70, v74, v75
	v_cvt_pk_bf16_f32 v71, v76, v77
	v_cvt_pk_bf16_f32 v72, v78, v79
	ds_read_b64_tr_b16 v[74:75], v80 offset:40960
	ds_read_b64_tr_b16 v[76:77], v80 offset:43008
	ds_read_b64_tr_b16 v[78:79], v80 offset:45056
	ds_read_b64_tr_b16 v[80:81], v80 offset:47104
	ds_read_b64_tr_b16 v[90:91], v96 offset:40960
	ds_read_b64_tr_b16 v[92:93], v96 offset:43008
	ds_read_b64_tr_b16 v[94:95], v96 offset:45056
	ds_read_b64_tr_b16 v[96:97], v96 offset:47104
	ds_read_b64_tr_b16 v[106:107], v99 offset:40960
	ds_read_b64_tr_b16 v[108:109], v99 offset:43008
	ds_read_b64_tr_b16 v[114:115], v99 offset:45056
	ds_read_b64_tr_b16 v[116:117], v99 offset:47104
	ds_read_b64_tr_b16 v[118:119], v98 offset:40960
	ds_read_b64_tr_b16 v[120:121], v98 offset:43008
	ds_read_b64_tr_b16 v[134:135], v98 offset:45056
	ds_read_b64_tr_b16 v[136:137], v98 offset:47104
	s_waitcnt lgkmcnt(10)
	v_mfma_f32_16x16x32_bf16 v[34:37], v[90:93], v[66:69], v[34:37]
	v_mov_b32_e32 v218, v212
	s_waitcnt lgkmcnt(6)
	v_mfma_f32_16x16x32_bf16 v[30:33], v[106:109], v[66:69], v[30:33]
	v_mfma_f32_16x16x32_bf16 v[38:41], v[74:77], v[66:69], v[38:41]
	v_mfma_f32_16x16x32_bf16 v[102:105], v[94:97], v[70:73], v[34:37]
	v_mfma_f32_16x16x32_bf16 v[34:37], v[106:109], v[82:85], v[50:53]
	s_waitcnt lgkmcnt(4)
	v_mfma_f32_16x16x32_bf16 v[106:109], v[114:117], v[70:73], v[30:33]
	s_waitcnt lgkmcnt(2)
	v_mfma_f32_16x16x32_bf16 v[30:33], v[118:121], v[82:85], v[46:49]
	v_mfma_f32_16x16x32_bf16 v[26:29], v[118:121], v[66:69], v[26:29]
	v_mfma_f32_16x16x32_bf16 v[62:65], v[74:77], v[82:85], v[62:65]
	v_mfma_f32_16x16x32_bf16 v[98:101], v[78:81], v[70:73], v[38:41]
	v_mfma_f32_16x16x32_bf16 v[38:41], v[90:93], v[82:85], v[54:57]
	s_waitcnt lgkmcnt(0)
	v_mfma_f32_16x16x32_bf16 v[130:133], v[134:137], v[86:89], v[30:33]
	v_mfma_f32_16x16x32_bf16 v[118:121], v[134:137], v[70:73], v[26:29]
	v_mfma_f32_16x16x32_bf16 v[26:29], v[22:25], v[82:85], v[58:61]
	v_mfma_f32_16x16x32_bf16 v[30:33], v[22:25], v[66:69], v[42:45]
	v_mfma_f32_16x16x32_bf16 v[110:113], v[78:81], v[86:89], v[62:65]
	v_mfma_f32_16x16x32_bf16 v[122:125], v[94:97], v[86:89], v[38:41]
	v_mfma_f32_16x16x32_bf16 v[126:129], v[114:117], v[86:89], v[34:37]
	v_mfma_f32_16x16x32_bf16 v[134:137], v[22:25], v[86:89], v[26:29]
	v_mfma_f32_16x16x32_bf16 v[114:117], v[22:25], v[70:73], v[30:33]

; #define LAS __attribute__((address_space(3)))
; #define SS_ISSUE(t, slot) do { LAS unsigned char* d_ = lbase + (slot) * 2 * TILEB; const size_t gb_ = (size_t)rowfn(t) * 256 + goff; \
;         __builtin_amdgcn_global_load_lds((const unsigned*)((const char*)Kg + gb_), (LAS unsigned*)d_, 16, 0, 0); \
;         __builtin_amdgcn_global_load_lds((const unsigned*)((const char*)Vg + gb_), (LAS unsigned*)(d_ + TILEB), 16, 0, 0); } while (0)
; template <int NB, class RowFn, class Compute>
; DEV void stream_stages_dma(Frame& F, int n, const bf16* Kg, const bf16* Vg, RowFn rowfn, Compute compute) {
;     ...
;     for (int i0 = 0, st = 0; i0 < n; i0 += NB, st ^= 1) {
;         asm volatile("s_waitcnt vmcnt(0)" ::: "memory");
;         __builtin_amdgcn_s_barrier(); asm volatile("" ::: "memory");
; #pragma unroll
;         for (int b = 0; b < NB; ++b) if (i0 + NB + b < n) SS_ISSUE(i0 + NB + b, (st ^ 1) * NB + b);
;         const LAS unsigned char* cur = F.lds + st * NB * 2 * TILEB;
; #pragma unroll
;         for (int b = 0; b < NB; ++b) if (i0 + b < n) compute(i0 + b, cur + b * 2 * TILEB, cur + b * 2 * TILEB + TILEB);
;     }
.LBB0_1248:
	s_add_i32 s24, s24, 12
	s_add_i32 s8, s26, -2
	s_cmp_ge_i32 s8, s23
	s_cbranch_scc1 .LBB0_1257
	s_mov_b32 s28, s26
	s_mov_b32 s8, s25
	s_branch .LBB0_1167
.LBB0_1252:
	s_cbranch_execz .LBB0_1187
	s_branch .LBB0_1195

; #define LAS __attribute__((address_space(3)))
; DEV void qk64(const LAS unsigned char* Kb, const AttnCtx& C, const ab8 (&qf)[2][2], f32x4 (&s)[2][4], float init0, float init1, bool a0, bool a1) {
;     ab8 k0[4], k1[4];
; #pragma unroll
;     for (int kt = 0; kt < 4; ++kt) { k0[kt] = *(const LAS ab8*)(Kb + swz(16 * kt + C.n, C.q4)); k1[kt] = *(const LAS ab8*)(Kb + swz(16 * kt + C.n, 4 + C.q4)); }
;     __builtin_amdgcn_sched_barrier(0);
; #pragma unroll
;     for (int kt = 0; kt < 4; ++kt) {
;         if (a0) { f32x4 c = {init0, init0, init0, init0}; c = __builtin_amdgcn_mfma_f32_16x16x32_bf16(k0[kt], qf[0][0], c, 0, 0, 0); s[0][kt] = __builtin_amdgcn_mfma_f32_16x16x32_bf16(k1[kt], qf[0][1], c, 0, 0, 0); }
;         if (a1) { f32x4 c = {init1, init1, init1, init1}; c = __builtin_amdgcn_mfma_f32_16x16x32_bf16(k0[kt], qf[1][0], c, 0, 0, 0); s[1][kt] = __builtin_amdgcn_mfma_f32_16x16x32_bf16(k1[kt], qf[1][1], c, 0, 0, 0); }
;     }
; }
; DEV void attn_unit_mfma(Frame& F, int qg, int kv) {
;     ...
;         const int it = i + iw0, p0 = t0 - 512 + 64 * it; const bool near = it >= 6; const float bi = near ? 0.f : C.b31;
;         f32x4 s[2][4]; qk64(Kb, C, qf, s, cinit(bi, m[0], true), cinit(bi, m[1], true), true, true);
;         ab8 pf[2][2], vf[4][2]; pv_load(Vb, C, vf); __builtin_amdgcn_sched_barrier(0);
; #pragma unroll
;         for (int g = 0; g < 2; ++g) { if (near) mask_bias<true, false>(s[g], C, C.tq[g], p0, 1, true); else if (it == 0) mask_bias<false, true>(s[g], C, C.tq[g], p0, 1, true);
;             ref_step(s[g], m[g], O[g], L[g], pf[g], true); }
;         pv_mma(C, vf, pf, O, L, true, true);
.LBB0_1283:
	s_mul_hi_u32 s24, s43, 0xaaaaaaab
	s_lshr_b32 s24, s24, 2
	s_mul_i32 s24, s24, 0x18000
	s_add_i32 s30, s38, s41
	v_subrev_u32_e32 v136, s24, v179
	v_subrev_u32_e32 v137, s24, v181
	v_subrev_u32_e32 v156, s24, v182
	v_subrev_u32_e32 v157, s24, v183
	v_subrev_u32_e32 v158, s24, v184
	v_subrev_u32_e32 v196, s24, v185
	v_subrev_u32_e32 v197, s24, v186
	v_subrev_u32_e32 v198, s24, v187
	v_subrev_u32_e32 v199, s24, v188
	v_subrev_u32_e32 v200, s24, v189
	v_subrev_u32_e32 v201, s24, v190
	v_subrev_u32_e32 v202, s24, v191
	v_subrev_u32_e32 v203, s24, v192
	v_subrev_u32_e32 v204, s24, v193
	v_subrev_u32_e32 v205, s24, v194
	v_subrev_u32_e32 v206, s24, v195
	v_subrev_u32_e32 v66, s24, v176
	v_subrev_u32_e32 v67, s24, v177
	s_add_i32 s24, s30, -5
	s_cmp_lt_i32 s24, 6
	s_cselect_b64 s[26:27], -1, 0
	s_add_i32 s24, s42, 0
	v_add_u32_e32 v86, s24, v67
	v_add_u32_e32 v94, s24, v66
	ds_read_b128 v[66:69], v86
	ds_read_b128 v[70:73], v86 offset:2048
	ds_read_b128 v[74:77], v94
	ds_read_b128 v[78:81], v94 offset:2048
	ds_read_b128 v[82:85], v86 offset:4096
	ds_read_b128 v[86:89], v86 offset:6144
	ds_read_b128 v[90:93], v94 offset:4096
	ds_read_b128 v[94:97], v94 offset:6144
	v_cmp_eq_f32_e64 s[28:29], s3, v134
	v_cmp_eq_f32_e64 s[24:25], s3, v135
	v_cndmask_b32_e64 v99, 0, v175, s[26:27]
	v_cndmask_b32_e64 v98, v134, 0, s[28:29]
	v_cndmask_b32_e64 v100, v135, 0, s[24:25]
	v_sub_f32_e32 v98, v99, v98
	v_sub_f32_e32 v144, v99, v100
	v_mov_b32_e32 v99, v98
	v_mov_b32_e32 v100, v98
	v_mov_b32_e32 v101, v98
	v_mov_b32_e32 v145, v144
	v_mov_b32_e32 v146, v144
	v_mov_b32_e32 v147, v144
	s_waitcnt lgkmcnt(0)
	v_mfma_f32_16x16x32_bf16 v[102:105], v[66:69], v[2:5], v[98:101]
	v_mfma_f32_16x16x32_bf16 v[66:69], v[66:69], v[10:13], v[144:147]
	v_mfma_f32_16x16x32_bf16 v[110:113], v[74:77], v[14:17], v[66:69]
	v_mfma_f32_16x16x32_bf16 v[66:69], v[70:73], v[2:5], v[98:101]
	v_mfma_f32_16x16x32_bf16 v[122:125], v[78:81], v[6:9], v[66:69]
	v_mfma_f32_16x16x32_bf16 v[66:69], v[70:73], v[10:13], v[144:147]
	v_add3_u32 v70, s42, v204, v180
	v_add3_u32 v72, s42, v203, v180
	ds_read_b64_tr_b16 v[70:71], v70
	ds_read_b64_tr_b16 v[72:73], v72
	v_mfma_f32_16x16x32_bf16 v[106:109], v[78:81], v[14:17], v[66:69]
	v_add3_u32 v78, s42, v200, v180
	v_add3_u32 v80, s42, v199, v180
	ds_read_b64_tr_b16 v[78:79], v78
	ds_read_b64_tr_b16 v[80:81], v80
	v_mfma_f32_16x16x32_bf16 v[66:69], v[82:85], v[2:5], v[98:101]
	v_mfma_f32_16x16x32_bf16 v[118:121], v[90:93], v[6:9], v[66:69]
	v_mfma_f32_16x16x32_bf16 v[66:69], v[82:85], v[10:13], v[144:147]
	v_add3_u32 v82, s42, v198, v180
	v_add3_u32 v84, s42, v197, v180
	ds_read_b64_tr_b16 v[82:83], v82
	ds_read_b64_tr_b16 v[84:85], v84
	v_mfma_f32_16x16x32_bf16 v[126:129], v[74:77], v[6:9], v[102:105]
	v_add3_u32 v74, s42, v202, v180
	v_add3_u32 v76, s42, v201, v180
	ds_read_b64_tr_b16 v[74:75], v74
	ds_read_b64_tr_b16 v[76:77], v76
	v_mfma_f32_16x16x32_bf16 v[102:105], v[90:93], v[14:17], v[66:69]
	v_add3_u32 v90, s42, v157, v180
	v_add3_u32 v92, s42, v156, v180
	ds_read_b64_tr_b16 v[90:91], v90
	ds_read_b64_tr_b16 v[92:93], v92
	v_mfma_f32_16x16x32_bf16 v[66:69], v[86:89], v[2:5], v[98:101]
	v_mfma_f32_16x16x32_bf16 v[114:117], v[94:97], v[6:9], v[66:69]
	v_mfma_f32_16x16x32_bf16 v[66:69], v[86:89], v[10:13], v[144:147]
	v_add3_u32 v86, s42, v196, v180
	v_add3_u32 v88, s42, v158, v180
	ds_read_b64_tr_b16 v[86:87], v86
	ds_read_b64_tr_b16 v[88:89], v88
	v_mfma_f32_16x16x32_bf16 v[98:101], v[94:97], v[14:17], v[66:69]
	v_add3_u32 v94, s42, v137, v180
	v_add3_u32 v96, s42, v136, v180
	ds_read_b64_tr_b16 v[94:95], v94
	ds_read_b64_tr_b16 v[96:97], v96
	v_add3_u32 v66, s42, v206, v180
	v_add3_u32 v68, s42, v205, v180
	ds_read_b64_tr_b16 v[66:67], v66
	ds_read_b64_tr_b16 v[68:69], v68
	s_cmp_eq_u32 s30, 5
	s_cselect_b64 s[30:31], -1, 0
	v_cndmask_b32_e64 v136, 0, 1, s[30:31]
	s_mov_b64 s[36:37], -1
	s_and_b64 vcc, exec, s[26:27]
	v_cmp_ne_u32_e64 s[30:31], 1, v136
	s_cbranch_vccz .LBB0_1287
	s_and_b64 vcc, exec, s[30:31]
	v_mov_b32_e32 v145, v129
	v_mov_b32_e32 v144, v128
	v_mov_b32_e32 v137, v127
	v_mov_b32_e32 v136, v126
	v_mov_b32_e32 v157, v125
	v_mov_b32_e32 v156, v124
	v_mov_b32_e32 v147, v123
	v_mov_b32_e32 v146, v122
	v_mov_b32_e32 v198, v121
	v_mov_b32_e32 v197, v120
	v_mov_b32_e32 v196, v119
	v_mov_b32_e32 v158, v118
	v_mov_b32_e32 v202, v117
	v_mov_b32_e32 v201, v116
	v_mov_b32_e32 v200, v115
	v_mov_b32_e32 v199, v114
	s_cbranch_vccnz .LBB0_1286
	v_add_u32_e32 v136, -4, v133
	v_cmp_gt_u32_e32 vcc, s73, v136
	v_add_u32_e32 v144, -6, v133
	v_add_u32_e32 v145, -7, v133
	v_cndmask_b32_e32 v136, v173, v126, vcc
	v_cmp_gt_u32_e32 vcc, s73, v144
	v_subrev_u32_e32 v146, 20, v133
	v_subrev_u32_e32 v156, 22, v133
	v_cndmask_b32_e32 v144, v173, v128, vcc
	v_cmp_gt_u32_e32 vcc, s73, v145
	v_subrev_u32_e32 v157, 23, v133
	v_subrev_u32_e32 v158, 36, v133
	v_cndmask_b32_e32 v145, v173, v129, vcc
	v_cmp_gt_u32_e32 vcc, s73, v146
	v_subrev_u32_e32 v197, 38, v133
	v_subrev_u32_e32 v198, 39, v133
	v_cndmask_b32_e32 v146, v173, v122, vcc
	v_cmp_gt_u32_e32 vcc, s73, v156
	v_subrev_u32_e32 v199, 52, v133
	v_subrev_u32_e32 v201, 54, v133
	v_cndmask_b32_e32 v156, v173, v124, vcc
	v_cmp_gt_u32_e32 vcc, s73, v157
	v_subrev_u32_e32 v202, 55, v133
	v_cndmask_b32_e64 v137, v173, v127, s[10:11]
	v_cndmask_b32_e32 v157, v173, v125, vcc
	v_cmp_gt_u32_e32 vcc, s73, v158
	v_cndmask_b32_e64 v147, v173, v123, s[18:19]
	v_cndmask_b32_e64 v196, v173, v119, s[8:9]
	v_cndmask_b32_e32 v158, v173, v118, vcc
	v_cmp_gt_u32_e32 vcc, s73, v197
	v_cndmask_b32_e64 v200, v173, v115, s[14:15]
	s_nop 0
	v_cndmask_b32_e32 v197, v173, v120, vcc
	v_cmp_gt_u32_e32 vcc, s73, v198
	s_nop 1
	v_cndmask_b32_e32 v198, v173, v121, vcc
	v_cmp_gt_u32_e32 vcc, s73, v199
	s_nop 1
	v_cndmask_b32_e32 v199, v173, v114, vcc
	v_cmp_gt_u32_e32 vcc, s73, v201
	s_nop 1
	v_cndmask_b32_e32 v201, v173, v116, vcc
	v_cmp_gt_u32_e32 vcc, s73, v202
	s_nop 1
	v_cndmask_b32_e32 v202, v173, v117, vcc
